# GEMM K-loops: removed the back-to-back s_setprio 0 / s_setprio 1 pairs between the two MFMA blocks of each super-phase
# baseline (speedup 1.0000x reference)
.LBB0_105:
	s_add_u32 s30, s0, 0xfff80080
	s_addc_u32 s31, s1, -1
	s_add_i32 s63, 0, 0x10000
	s_cmp_eq_u32 s62, 28
	s_cselect_b32 s51, s41, s31
	s_cselect_b32 s50, s47, s30
	v_add_u32_e32 v150, s63, v153
	s_cselect_b32 s49, s39, s61
	s_cselect_b32 s48, s55, s60
	s_add_i32 s64, 0, 0x14000
	ds_read_b128 v[146:149], v150
	ds_read_b128 v[156:159], v150 offset:1024
	ds_read_b128 v[160:163], v150 offset:2048
	ds_read_b128 v[174:177], v150 offset:3072
	v_add_u32_e32 v150, s64, v153
	ds_read_b128 v[178:181], v150
	ds_read_b128 v[182:185], v150 offset:1024
	ds_read_b128 v[186:189], v150 offset:2048
	ds_read_b128 v[190:193], v150 offset:3072
	v_lshl_add_u64 v[150:151], s[0:1], 0, v[144:145]
	s_add_i32 m0, s9, 0xc000
	ds_read_b128 v[194:197], v155
	ds_read_b128 v[198:201], v155 offset:1024
	ds_read_b128 v[202:205], v155 offset:2048
	ds_read_b128 v[206:209], v155 offset:3072
	ds_read_b128 v[218:221], v155 offset:4096
	ds_read_b128 v[222:225], v155 offset:5120
	ds_read_b128 v[226:229], v155 offset:6144
	ds_read_b128 v[230:233], v155 offset:7168
	global_load_lds_dwordx4 v[150:151], off
	v_lshl_add_u64 v[150:151], s[0:1], 0, v[142:143]
	s_add_i32 m0, s9, 0xe000
	s_nop 0
	global_load_lds_dwordx4 v[150:151], off
	s_waitcnt vmcnt(8)
	s_waitcnt lgkmcnt(0)
	s_barrier
	s_setprio 1
	s_waitcnt lgkmcnt(0)
	v_mfma_f32_16x16x32_bf16 v[70:73], v[146:149], v[194:197], v[70:73]
	v_mfma_f32_16x16x32_bf16 v[66:69], v[160:163], v[194:197], v[66:69]
	v_mfma_f32_16x16x32_bf16 v[62:65], v[146:149], v[202:205], v[62:65]
	v_mfma_f32_16x16x32_bf16 v[58:61], v[160:163], v[202:205], v[58:61]
	v_mfma_f32_16x16x32_bf16 v[50:53], v[146:149], v[218:221], v[50:53]
	v_mfma_f32_16x16x32_bf16 v[46:49], v[160:163], v[218:221], v[46:49]
	v_mfma_f32_16x16x32_bf16 v[42:45], v[146:149], v[226:229], v[42:45]
	v_mfma_f32_16x16x32_bf16 v[38:41], v[160:163], v[226:229], v[38:41]
	v_mfma_f32_16x16x32_bf16 v[70:73], v[156:159], v[198:201], v[70:73]
	v_mfma_f32_16x16x32_bf16 v[66:69], v[174:177], v[198:201], v[66:69]
	v_mfma_f32_16x16x32_bf16 v[62:65], v[156:159], v[206:209], v[62:65]
	v_mfma_f32_16x16x32_bf16 v[58:61], v[174:177], v[206:209], v[58:61]
	v_mfma_f32_16x16x32_bf16 v[50:53], v[156:159], v[222:225], v[50:53]
	v_mfma_f32_16x16x32_bf16 v[46:49], v[174:177], v[222:225], v[46:49]
	v_mfma_f32_16x16x32_bf16 v[42:45], v[156:159], v[230:233], v[42:45]
	v_mfma_f32_16x16x32_bf16 v[38:41], v[174:177], v[230:233], v[38:41]
	v_mfma_f32_16x16x32_bf16 v[126:129], v[178:181], v[194:197], v[126:129]
	v_mfma_f32_16x16x32_bf16 v[122:125], v[186:189], v[194:197], v[122:125]
	v_mfma_f32_16x16x32_bf16 v[118:121], v[178:181], v[202:205], v[118:121]
	v_mfma_f32_16x16x32_bf16 v[114:117], v[186:189], v[202:205], v[114:117]
	v_mfma_f32_16x16x32_bf16 v[110:113], v[178:181], v[218:221], v[110:113]
	v_mfma_f32_16x16x32_bf16 v[106:109], v[186:189], v[218:221], v[106:109]
	v_mfma_f32_16x16x32_bf16 v[102:105], v[178:181], v[226:229], v[102:105]
	v_mfma_f32_16x16x32_bf16 v[98:101], v[186:189], v[226:229], v[98:101]
	v_mfma_f32_16x16x32_bf16 v[126:129], v[182:185], v[198:201], v[126:129]
	v_mfma_f32_16x16x32_bf16 v[122:125], v[190:193], v[198:201], v[122:125]
	v_mfma_f32_16x16x32_bf16 v[118:121], v[182:185], v[206:209], v[118:121]
	v_mfma_f32_16x16x32_bf16 v[114:117], v[190:193], v[206:209], v[114:117]
	v_mfma_f32_16x16x32_bf16 v[110:113], v[182:185], v[222:225], v[110:113]
	v_mfma_f32_16x16x32_bf16 v[106:109], v[190:193], v[222:225], v[106:109]
	v_mfma_f32_16x16x32_bf16 v[102:105], v[182:185], v[230:233], v[102:105]
	v_mfma_f32_16x16x32_bf16 v[98:101], v[190:193], v[230:233], v[98:101]
	s_setprio 0
	s_barrier
	s_add_i32 s30, s63, s8
	v_lshl_add_u64 v[150:151], s[48:49], 0, v[134:135]
	s_mov_b32 m0, s30
	ds_read_b128 v[194:197], v155 offset:16384
	ds_read_b128 v[198:201], v155 offset:17408
	ds_read_b128 v[202:205], v155 offset:18432
	ds_read_b128 v[206:209], v155 offset:19456
	ds_read_b128 v[218:221], v155 offset:20480
	ds_read_b128 v[222:225], v155 offset:21504
	ds_read_b128 v[226:229], v155 offset:22528
	ds_read_b128 v[230:233], v155 offset:23552
	global_load_lds_dwordx4 v[150:151], off
	s_add_i32 m0, s30, 0x2000
	s_add_u32 s30, s48, 0x80000
	v_lshl_add_u64 v[164:165], s[48:49], 0, v[130:131]
	s_addc_u32 s31, s49, 0
	s_add_i32 s63, s64, s8
	global_load_lds_dwordx4 v[164:165], off
	v_lshl_add_u64 v[166:167], s[30:31], 0, v[134:135]
	s_mov_b32 m0, s63
	v_lshl_add_u64 v[170:171], s[50:51], 0, v[132:133]
	global_load_lds_dwordx4 v[166:167], off
	v_lshl_add_u64 v[166:167], s[30:31], 0, v[130:131]
	s_add_i32 m0, s63, 0x2000
	s_nop 0
	global_load_lds_dwordx4 v[166:167], off
	v_lshl_add_u64 v[166:167], s[50:51], 0, v[136:137]
	s_mov_b32 m0, s9
	s_nop 0
	global_load_lds_dwordx4 v[166:167], off
	s_mov_b32 m0, s28
	s_nop 0
	global_load_lds_dwordx4 v[170:171], off
	s_waitcnt vmcnt(8)
	s_waitcnt lgkmcnt(0)
	s_barrier
	s_setprio 1
	s_waitcnt lgkmcnt(0)
	v_mfma_f32_16x16x32_bf16 v[30:33], v[146:149], v[194:197], v[30:33]
	v_mfma_f32_16x16x32_bf16 v[26:29], v[160:163], v[194:197], v[26:29]
	v_mfma_f32_16x16x32_bf16 v[22:25], v[146:149], v[202:205], v[22:25]
	v_mfma_f32_16x16x32_bf16 v[18:21], v[160:163], v[202:205], v[18:21]
	v_mfma_f32_16x16x32_bf16 v[14:17], v[146:149], v[218:221], v[14:17]
	v_mfma_f32_16x16x32_bf16 v[10:13], v[160:163], v[218:221], v[10:13]
	v_mfma_f32_16x16x32_bf16 v[6:9], v[146:149], v[226:229], v[6:9]
	v_mfma_f32_16x16x32_bf16 v[2:5], v[160:163], v[226:229], v[2:5]
	v_mfma_f32_16x16x32_bf16 v[30:33], v[156:159], v[198:201], v[30:33]
	v_mfma_f32_16x16x32_bf16 v[26:29], v[174:177], v[198:201], v[26:29]
	v_mfma_f32_16x16x32_bf16 v[22:25], v[156:159], v[206:209], v[22:25]
	v_mfma_f32_16x16x32_bf16 v[18:21], v[174:177], v[206:209], v[18:21]
	v_mfma_f32_16x16x32_bf16 v[14:17], v[156:159], v[222:225], v[14:17]
	v_mfma_f32_16x16x32_bf16 v[10:13], v[174:177], v[222:225], v[10:13]
	v_mfma_f32_16x16x32_bf16 v[6:9], v[156:159], v[230:233], v[6:9]
	v_mfma_f32_16x16x32_bf16 v[2:5], v[174:177], v[230:233], v[2:5]
	v_mfma_f32_16x16x32_bf16 v[94:97], v[178:181], v[194:197], v[94:97]
	v_mfma_f32_16x16x32_bf16 v[90:93], v[186:189], v[194:197], v[90:93]
	v_mfma_f32_16x16x32_bf16 v[86:89], v[178:181], v[202:205], v[86:89]
	v_mfma_f32_16x16x32_bf16 v[82:85], v[186:189], v[202:205], v[82:85]
	v_mfma_f32_16x16x32_bf16 v[78:81], v[178:181], v[218:221], v[78:81]
	v_mfma_f32_16x16x32_bf16 v[74:77], v[186:189], v[218:221], v[74:77]
	v_mfma_f32_16x16x32_bf16 v[54:57], v[178:181], v[226:229], v[54:57]
	v_mfma_f32_16x16x32_bf16 v[34:37], v[186:189], v[226:229], v[34:37]
	v_mfma_f32_16x16x32_bf16 v[94:97], v[182:185], v[198:201], v[94:97]
	v_mfma_f32_16x16x32_bf16 v[90:93], v[190:193], v[198:201], v[90:93]
	v_mfma_f32_16x16x32_bf16 v[86:89], v[182:185], v[206:209], v[86:89]
	v_mfma_f32_16x16x32_bf16 v[82:85], v[190:193], v[206:209], v[82:85]
	v_mfma_f32_16x16x32_bf16 v[78:81], v[182:185], v[222:225], v[78:81]
	v_mfma_f32_16x16x32_bf16 v[74:77], v[190:193], v[222:225], v[74:77]
	v_mfma_f32_16x16x32_bf16 v[54:57], v[182:185], v[230:233], v[54:57]
	v_mfma_f32_16x16x32_bf16 v[34:37], v[190:193], v[230:233], v[34:37]
	s_setprio 0
	s_barrier
	s_add_i32 s63, 0, 0x18000
	v_add_u32_e32 v172, s63, v153
	s_add_i32 s64, 0, 0x1c000
	ds_read_b128 v[146:149], v172
	ds_read_b128 v[156:159], v172 offset:1024
	ds_read_b128 v[160:163], v172 offset:2048
	ds_read_b128 v[174:177], v172 offset:3072
	v_add_u32_e32 v172, s64, v153
	ds_read_b128 v[178:181], v172
	ds_read_b128 v[182:185], v172 offset:1024
	ds_read_b128 v[186:189], v172 offset:2048
	ds_read_b128 v[190:193], v172 offset:3072
	s_add_u32 s30, s50, 0x80000
	s_addc_u32 s31, s51, 0
	s_mov_b32 m0, s29
	v_lshl_add_u64 v[172:173], s[30:31], 0, v[136:137]
	ds_read_b128 v[194:197], v155 offset:32768
	ds_read_b128 v[198:201], v155 offset:33792
	ds_read_b128 v[202:205], v155 offset:34816
	ds_read_b128 v[206:209], v155 offset:35840
	ds_read_b128 v[218:221], v155 offset:36864
	ds_read_b128 v[222:225], v155 offset:37888
	ds_read_b128 v[226:229], v155 offset:38912
	ds_read_b128 v[230:233], v155 offset:39936
	global_load_lds_dwordx4 v[172:173], off
	v_lshl_add_u64 v[172:173], s[30:31], 0, v[132:133]
	s_mov_b32 m0, s35
	s_nop 0
	global_load_lds_dwordx4 v[172:173], off
	s_waitcnt vmcnt(8)
	s_waitcnt lgkmcnt(0)
	s_barrier
	s_setprio 1
	s_waitcnt lgkmcnt(0)
	v_mfma_f32_16x16x32_bf16 v[70:73], v[146:149], v[194:197], v[70:73]
	v_mfma_f32_16x16x32_bf16 v[66:69], v[160:163], v[194:197], v[66:69]
	v_mfma_f32_16x16x32_bf16 v[62:65], v[146:149], v[202:205], v[62:65]
	v_mfma_f32_16x16x32_bf16 v[58:61], v[160:163], v[202:205], v[58:61]
	v_mfma_f32_16x16x32_bf16 v[50:53], v[146:149], v[218:221], v[50:53]
	v_mfma_f32_16x16x32_bf16 v[46:49], v[160:163], v[218:221], v[46:49]
	v_mfma_f32_16x16x32_bf16 v[42:45], v[146:149], v[226:229], v[42:45]
	v_mfma_f32_16x16x32_bf16 v[38:41], v[160:163], v[226:229], v[38:41]
	v_mfma_f32_16x16x32_bf16 v[70:73], v[156:159], v[198:201], v[70:73]
	v_mfma_f32_16x16x32_bf16 v[66:69], v[174:177], v[198:201], v[66:69]
	v_mfma_f32_16x16x32_bf16 v[62:65], v[156:159], v[206:209], v[62:65]
	v_mfma_f32_16x16x32_bf16 v[58:61], v[174:177], v[206:209], v[58:61]
	v_mfma_f32_16x16x32_bf16 v[50:53], v[156:159], v[222:225], v[50:53]
	v_mfma_f32_16x16x32_bf16 v[46:49], v[174:177], v[222:225], v[46:49]
	v_mfma_f32_16x16x32_bf16 v[42:45], v[156:159], v[230:233], v[42:45]
	v_mfma_f32_16x16x32_bf16 v[38:41], v[174:177], v[230:233], v[38:41]
	v_mfma_f32_16x16x32_bf16 v[126:129], v[178:181], v[194:197], v[126:129]
	v_mfma_f32_16x16x32_bf16 v[122:125], v[186:189], v[194:197], v[122:125]
	v_mfma_f32_16x16x32_bf16 v[118:121], v[178:181], v[202:205], v[118:121]
	v_mfma_f32_16x16x32_bf16 v[114:117], v[186:189], v[202:205], v[114:117]
	v_mfma_f32_16x16x32_bf16 v[110:113], v[178:181], v[218:221], v[110:113]
	v_mfma_f32_16x16x32_bf16 v[106:109], v[186:189], v[218:221], v[106:109]
	v_mfma_f32_16x16x32_bf16 v[102:105], v[178:181], v[226:229], v[102:105]
	v_mfma_f32_16x16x32_bf16 v[98:101], v[186:189], v[226:229], v[98:101]
	v_mfma_f32_16x16x32_bf16 v[126:129], v[182:185], v[198:201], v[126:129]
	v_mfma_f32_16x16x32_bf16 v[122:125], v[190:193], v[198:201], v[122:125]
	v_mfma_f32_16x16x32_bf16 v[118:121], v[182:185], v[206:209], v[118:121]
	v_mfma_f32_16x16x32_bf16 v[114:117], v[190:193], v[206:209], v[114:117]
	v_mfma_f32_16x16x32_bf16 v[110:113], v[182:185], v[222:225], v[110:113]
	v_mfma_f32_16x16x32_bf16 v[106:109], v[190:193], v[222:225], v[106:109]
	v_mfma_f32_16x16x32_bf16 v[102:105], v[182:185], v[230:233], v[102:105]
	v_mfma_f32_16x16x32_bf16 v[98:101], v[190:193], v[230:233], v[98:101]
	s_setprio 0
	s_barrier
	s_add_i32 s30, s63, s8
	v_lshl_add_u64 v[150:151], v[150:151], 0, s[24:25]
	s_mov_b32 m0, s30
	ds_read_b128 v[194:197], v155 offset:49152
	ds_read_b128 v[198:201], v155 offset:50176
	ds_read_b128 v[202:205], v155 offset:51200
	ds_read_b128 v[206:209], v155 offset:52224
	ds_read_b128 v[218:221], v155 offset:53248
	ds_read_b128 v[222:225], v155 offset:54272
	ds_read_b128 v[226:229], v155 offset:55296
	ds_read_b128 v[230:233], v155 offset:56320
	global_load_lds_dwordx4 v[150:151], off
	s_add_i32 m0, s30, 0x2000
	s_add_u32 s30, s48, 0x80080
	v_lshl_add_u64 v[150:151], v[164:165], 0, s[24:25]
	s_addc_u32 s31, s49, 0
	s_add_i32 s48, s64, s8
	global_load_lds_dwordx4 v[150:151], off
	v_lshl_add_u64 v[150:151], s[30:31], 0, v[134:135]
	s_mov_b32 m0, s48
	s_nop 0
	global_load_lds_dwordx4 v[150:151], off
	v_lshl_add_u64 v[150:151], s[30:31], 0, v[130:131]
	s_add_i32 m0, s48, 0x2000
	s_nop 0
	global_load_lds_dwordx4 v[150:151], off
	v_lshl_add_u64 v[150:151], v[166:167], 0, s[24:25]
	s_mov_b32 m0, s52
	s_nop 0
	global_load_lds_dwordx4 v[150:151], off
	v_lshl_add_u64 v[150:151], v[170:171], 0, s[24:25]
	s_mov_b32 m0, s53
	s_nop 0
	global_load_lds_dwordx4 v[150:151], off
	s_waitcnt vmcnt(8)
	s_waitcnt lgkmcnt(0)
	s_barrier
	s_setprio 1
	s_waitcnt lgkmcnt(0)
	v_mfma_f32_16x16x32_bf16 v[30:33], v[146:149], v[194:197], v[30:33]
	v_mfma_f32_16x16x32_bf16 v[26:29], v[160:163], v[194:197], v[26:29]
	v_mfma_f32_16x16x32_bf16 v[22:25], v[146:149], v[202:205], v[22:25]
	v_mfma_f32_16x16x32_bf16 v[18:21], v[160:163], v[202:205], v[18:21]
	v_mfma_f32_16x16x32_bf16 v[14:17], v[146:149], v[218:221], v[14:17]
	v_mfma_f32_16x16x32_bf16 v[10:13], v[160:163], v[218:221], v[10:13]
	v_mfma_f32_16x16x32_bf16 v[6:9], v[146:149], v[226:229], v[6:9]
	v_mfma_f32_16x16x32_bf16 v[2:5], v[160:163], v[226:229], v[2:5]
	v_mfma_f32_16x16x32_bf16 v[30:33], v[156:159], v[198:201], v[30:33]
	v_mfma_f32_16x16x32_bf16 v[26:29], v[174:177], v[198:201], v[26:29]
	v_mfma_f32_16x16x32_bf16 v[22:25], v[156:159], v[206:209], v[22:25]
	v_mfma_f32_16x16x32_bf16 v[18:21], v[174:177], v[206:209], v[18:21]
	v_mfma_f32_16x16x32_bf16 v[14:17], v[156:159], v[222:225], v[14:17]
	v_mfma_f32_16x16x32_bf16 v[10:13], v[174:177], v[222:225], v[10:13]
	v_mfma_f32_16x16x32_bf16 v[6:9], v[156:159], v[230:233], v[6:9]
	v_mfma_f32_16x16x32_bf16 v[2:5], v[174:177], v[230:233], v[2:5]
	v_mfma_f32_16x16x32_bf16 v[94:97], v[178:181], v[194:197], v[94:97]
	v_mfma_f32_16x16x32_bf16 v[90:93], v[186:189], v[194:197], v[90:93]
	v_mfma_f32_16x16x32_bf16 v[86:89], v[178:181], v[202:205], v[86:89]
	v_mfma_f32_16x16x32_bf16 v[82:85], v[186:189], v[202:205], v[82:85]
	v_mfma_f32_16x16x32_bf16 v[78:81], v[178:181], v[218:221], v[78:81]
	v_mfma_f32_16x16x32_bf16 v[74:77], v[186:189], v[218:221], v[74:77]
	v_mfma_f32_16x16x32_bf16 v[54:57], v[178:181], v[226:229], v[54:57]
	v_mfma_f32_16x16x32_bf16 v[34:37], v[186:189], v[226:229], v[34:37]
	v_mfma_f32_16x16x32_bf16 v[94:97], v[182:185], v[198:201], v[94:97]
	v_mfma_f32_16x16x32_bf16 v[90:93], v[190:193], v[198:201], v[90:93]
	v_mfma_f32_16x16x32_bf16 v[86:89], v[182:185], v[206:209], v[86:89]
	v_mfma_f32_16x16x32_bf16 v[82:85], v[190:193], v[206:209], v[82:85]
	v_mfma_f32_16x16x32_bf16 v[78:81], v[182:185], v[222:225], v[78:81]
	v_mfma_f32_16x16x32_bf16 v[74:77], v[190:193], v[222:225], v[74:77]
	v_mfma_f32_16x16x32_bf16 v[54:57], v[182:185], v[230:233], v[54:57]
	v_mfma_f32_16x16x32_bf16 v[34:37], v[190:193], v[230:233], v[34:37]
	s_setprio 0
	s_barrier
	s_add_i32 s62, s62, 2
	s_add_u32 s60, s60, 0x100
	s_addc_u32 s61, s61, 0
	s_add_u32 s0, s0, 0x100
	s_addc_u32 s1, s1, 0
	s_cmp_gt_u32 s62, 29
	s_cbranch_scc0 .LBB0_105
	s_and_b64 vcc, exec, s[16:17]
	s_cbranch_vccz .LBB0_108
	s_barrier

.LBB0_585:
	s_add_u32 s30, s16, s50
	s_addc_u32 s31, s17, s51
	s_add_u32 s30, s30, 0x100
	s_addc_u32 s31, s31, 0
	s_add_u32 s52, s28, s50
	s_addc_u32 s53, s29, s51
	s_cmpk_eq_i32 s50, 0x1700
	s_cselect_b32 s61, s1, s31
	s_cselect_b32 s60, s0, s30
	s_cselect_b32 s53, s41, s53
	s_cselect_b32 s52, s40, s52
	s_add_i32 s30, 0, 0x10000
	v_add_u32_e32 v0, s30, v162
	s_add_i32 s54, 0, 0x14000
	ds_read_b128 v[132:135], v0
	ds_read_b128 v[136:139], v0 offset:1024
	ds_read_b128 v[170:173], v0 offset:2048
	ds_read_b128 v[174:177], v0 offset:3072
	v_add_u32_e32 v0, s54, v162
	ds_read_b128 v[178:181], v0
	ds_read_b128 v[182:185], v0 offset:1024
	ds_read_b128 v[186:189], v0 offset:2048
	ds_read_b128 v[190:193], v0 offset:3072
	v_lshl_add_u64 v[2:3], v[156:157], 0, s[50:51]
	s_add_i32 m0, s35, 0xc000
	ds_read_b128 v[194:197], v165
	ds_read_b128 v[198:201], v165 offset:1024
	ds_read_b128 v[202:205], v165 offset:2048
	ds_read_b128 v[206:209], v165 offset:3072
	ds_read_b128 v[210:213], v165 offset:4096
	ds_read_b128 v[214:217], v165 offset:5120
	ds_read_b128 v[218:221], v165 offset:6144
	ds_read_b128 v[222:225], v165 offset:7168
	global_load_lds_dwordx4 v[2:3], off
	v_lshl_add_u64 v[2:3], v[154:155], 0, s[50:51]
	s_add_i32 m0, s35, 0xe000
	s_nop 0
	global_load_lds_dwordx4 v[2:3], off
	s_waitcnt vmcnt(8)
	s_waitcnt lgkmcnt(0)
	s_barrier
	s_setprio 1
	s_waitcnt lgkmcnt(0)
	v_mfma_f32_16x16x32_bf16 v[128:131], v[132:135], v[194:197], v[128:131]
	v_mfma_f32_16x16x32_bf16 v[124:127], v[170:173], v[194:197], v[124:127]
	v_mfma_f32_16x16x32_bf16 v[112:115], v[132:135], v[202:205], v[112:115]
	v_mfma_f32_16x16x32_bf16 v[108:111], v[170:173], v[202:205], v[108:111]
	v_mfma_f32_16x16x32_bf16 v[96:99], v[132:135], v[210:213], v[96:99]
	v_mfma_f32_16x16x32_bf16 v[92:95], v[170:173], v[210:213], v[92:95]
	v_mfma_f32_16x16x32_bf16 v[80:83], v[132:135], v[218:221], v[80:83]
	v_mfma_f32_16x16x32_bf16 v[76:79], v[170:173], v[218:221], v[76:79]
	v_mfma_f32_16x16x32_bf16 v[128:131], v[136:139], v[198:201], v[128:131]
	v_mfma_f32_16x16x32_bf16 v[124:127], v[174:177], v[198:201], v[124:127]
	v_mfma_f32_16x16x32_bf16 v[112:115], v[136:139], v[206:209], v[112:115]
	v_mfma_f32_16x16x32_bf16 v[108:111], v[174:177], v[206:209], v[108:111]
	v_mfma_f32_16x16x32_bf16 v[96:99], v[136:139], v[214:217], v[96:99]
	v_mfma_f32_16x16x32_bf16 v[92:95], v[174:177], v[214:217], v[92:95]
	v_mfma_f32_16x16x32_bf16 v[80:83], v[136:139], v[222:225], v[80:83]
	v_mfma_f32_16x16x32_bf16 v[76:79], v[174:177], v[222:225], v[76:79]
	v_mfma_f32_16x16x32_bf16 v[120:123], v[178:181], v[194:197], v[120:123]
	v_mfma_f32_16x16x32_bf16 v[116:119], v[186:189], v[194:197], v[116:119]
	v_mfma_f32_16x16x32_bf16 v[104:107], v[178:181], v[202:205], v[104:107]
	v_mfma_f32_16x16x32_bf16 v[100:103], v[186:189], v[202:205], v[100:103]
	v_mfma_f32_16x16x32_bf16 v[88:91], v[178:181], v[210:213], v[88:91]
	v_mfma_f32_16x16x32_bf16 v[84:87], v[186:189], v[210:213], v[84:87]
	v_mfma_f32_16x16x32_bf16 v[72:75], v[178:181], v[218:221], v[72:75]
	v_mfma_f32_16x16x32_bf16 v[68:71], v[186:189], v[218:221], v[68:71]
	v_mfma_f32_16x16x32_bf16 v[120:123], v[182:185], v[198:201], v[120:123]
	v_mfma_f32_16x16x32_bf16 v[116:119], v[190:193], v[198:201], v[116:119]
	v_mfma_f32_16x16x32_bf16 v[104:107], v[182:185], v[206:209], v[104:107]
	v_mfma_f32_16x16x32_bf16 v[100:103], v[190:193], v[206:209], v[100:103]
	v_mfma_f32_16x16x32_bf16 v[88:91], v[182:185], v[214:217], v[88:91]
	v_mfma_f32_16x16x32_bf16 v[84:87], v[190:193], v[214:217], v[84:87]
	v_mfma_f32_16x16x32_bf16 v[72:75], v[182:185], v[222:225], v[72:75]
	v_mfma_f32_16x16x32_bf16 v[68:71], v[190:193], v[222:225], v[68:71]
	s_setprio 0
	s_barrier
	s_add_i32 s30, s30, s18
	v_lshl_add_u64 v[158:159], s[52:53], 0, v[144:145]
	s_mov_b32 m0, s30
	ds_read_b128 v[194:197], v165 offset:16384
	ds_read_b128 v[198:201], v165 offset:17408
	ds_read_b128 v[202:205], v165 offset:18432
	ds_read_b128 v[206:209], v165 offset:19456
	ds_read_b128 v[210:213], v165 offset:20480
	ds_read_b128 v[214:217], v165 offset:21504
	ds_read_b128 v[218:221], v165 offset:22528
	ds_read_b128 v[222:225], v165 offset:23552
	global_load_lds_dwordx4 v[158:159], off
	s_add_i32 m0, s30, 0x2000
	s_add_u32 s30, s52, 0xc0000
	v_lshl_add_u64 v[166:167], s[52:53], 0, v[140:141]
	s_addc_u32 s31, s53, 0
	s_add_i32 s54, s54, s18
	global_load_lds_dwordx4 v[166:167], off
	v_lshl_add_u64 v[2:3], s[30:31], 0, v[144:145]
	s_mov_b32 m0, s54
	v_lshl_add_u64 v[226:227], s[60:61], 0, v[146:147]
	global_load_lds_dwordx4 v[2:3], off
	v_lshl_add_u64 v[2:3], s[30:31], 0, v[140:141]
	s_add_i32 m0, s54, 0x2000
	v_lshl_add_u64 v[228:229], s[60:61], 0, v[142:143]
	global_load_lds_dwordx4 v[2:3], off
	s_mov_b32 m0, s35
	s_nop 0
	global_load_lds_dwordx4 v[226:227], off
	s_mov_b32 m0, s62
	s_nop 0
	global_load_lds_dwordx4 v[228:229], off
	s_waitcnt vmcnt(8)
	s_waitcnt lgkmcnt(0)
	s_barrier
	s_setprio 1
	s_waitcnt lgkmcnt(0)
	v_mfma_f32_16x16x32_bf16 v[64:67], v[132:135], v[194:197], v[64:67]
	v_mfma_f32_16x16x32_bf16 v[60:63], v[170:173], v[194:197], v[60:63]
	v_mfma_f32_16x16x32_bf16 v[48:51], v[132:135], v[202:205], v[48:51]
	v_mfma_f32_16x16x32_bf16 v[44:47], v[170:173], v[202:205], v[44:47]
	v_mfma_f32_16x16x32_bf16 v[32:35], v[132:135], v[210:213], v[32:35]
	v_mfma_f32_16x16x32_bf16 v[28:31], v[170:173], v[210:213], v[28:31]
	v_mfma_f32_16x16x32_bf16 v[16:19], v[132:135], v[218:221], v[16:19]
	v_mfma_f32_16x16x32_bf16 v[12:15], v[170:173], v[218:221], v[12:15]
	v_mfma_f32_16x16x32_bf16 v[64:67], v[136:139], v[198:201], v[64:67]
	v_mfma_f32_16x16x32_bf16 v[60:63], v[174:177], v[198:201], v[60:63]
	v_mfma_f32_16x16x32_bf16 v[48:51], v[136:139], v[206:209], v[48:51]
	v_mfma_f32_16x16x32_bf16 v[44:47], v[174:177], v[206:209], v[44:47]
	v_mfma_f32_16x16x32_bf16 v[32:35], v[136:139], v[214:217], v[32:35]
	v_mfma_f32_16x16x32_bf16 v[28:31], v[174:177], v[214:217], v[28:31]
	v_mfma_f32_16x16x32_bf16 v[16:19], v[136:139], v[222:225], v[16:19]
	v_mfma_f32_16x16x32_bf16 v[12:15], v[174:177], v[222:225], v[12:15]
	v_mfma_f32_16x16x32_bf16 v[56:59], v[178:181], v[194:197], v[56:59]
	v_mfma_f32_16x16x32_bf16 v[52:55], v[186:189], v[194:197], v[52:55]
	v_mfma_f32_16x16x32_bf16 v[40:43], v[178:181], v[202:205], v[40:43]
	v_mfma_f32_16x16x32_bf16 v[36:39], v[186:189], v[202:205], v[36:39]
	v_mfma_f32_16x16x32_bf16 v[24:27], v[178:181], v[210:213], v[24:27]
	v_mfma_f32_16x16x32_bf16 v[20:23], v[186:189], v[210:213], v[20:23]
	v_mfma_f32_16x16x32_bf16 v[8:11], v[178:181], v[218:221], v[8:11]
	v_mfma_f32_16x16x32_bf16 v[2:5], v[186:189], v[218:221], v[4:7]
	v_mfma_f32_16x16x32_bf16 v[56:59], v[182:185], v[198:201], v[56:59]
	v_mfma_f32_16x16x32_bf16 v[52:55], v[190:193], v[198:201], v[52:55]
	v_mfma_f32_16x16x32_bf16 v[40:43], v[182:185], v[206:209], v[40:43]
	v_mfma_f32_16x16x32_bf16 v[36:39], v[190:193], v[206:209], v[36:39]
	v_mfma_f32_16x16x32_bf16 v[24:27], v[182:185], v[214:217], v[24:27]
	v_mfma_f32_16x16x32_bf16 v[20:23], v[190:193], v[214:217], v[20:23]
	v_mfma_f32_16x16x32_bf16 v[8:11], v[182:185], v[222:225], v[8:11]
	v_mfma_f32_16x16x32_bf16 v[2:5], v[190:193], v[222:225], v[2:5]
	s_setprio 0
	s_barrier
	s_add_i32 s54, 0, 0x18000
	v_add_u32_e32 v0, s54, v162
	s_add_i32 s55, 0, 0x1c000
	ds_read_b128 v[132:135], v0
	ds_read_b128 v[136:139], v0 offset:1024
	ds_read_b128 v[170:173], v0 offset:2048
	ds_read_b128 v[174:177], v0 offset:3072
	v_add_u32_e32 v0, s55, v162
	ds_read_b128 v[178:181], v0
	ds_read_b128 v[182:185], v0 offset:1024
	ds_read_b128 v[186:189], v0 offset:2048
	ds_read_b128 v[190:193], v0 offset:3072
	s_add_u32 s30, s60, 0xc0000
	s_addc_u32 s31, s61, 0
	s_mov_b32 m0, s63
	v_lshl_add_u64 v[6:7], s[30:31], 0, v[146:147]
	ds_read_b128 v[194:197], v165 offset:32768
	ds_read_b128 v[198:201], v165 offset:33792
	ds_read_b128 v[202:205], v165 offset:34816
	ds_read_b128 v[206:209], v165 offset:35840
	ds_read_b128 v[210:213], v165 offset:36864
	ds_read_b128 v[214:217], v165 offset:37888
	ds_read_b128 v[218:221], v165 offset:38912
	ds_read_b128 v[222:225], v165 offset:39936
	global_load_lds_dwordx4 v[6:7], off
	v_lshl_add_u64 v[6:7], s[30:31], 0, v[142:143]
	s_mov_b32 m0, s64
	s_nop 0
	global_load_lds_dwordx4 v[6:7], off
	s_waitcnt vmcnt(8)
	s_waitcnt lgkmcnt(0)
	s_barrier
	s_setprio 1
	s_waitcnt lgkmcnt(0)
	v_mfma_f32_16x16x32_bf16 v[128:131], v[132:135], v[194:197], v[128:131]
	v_mfma_f32_16x16x32_bf16 v[124:127], v[170:173], v[194:197], v[124:127]
	v_mfma_f32_16x16x32_bf16 v[112:115], v[132:135], v[202:205], v[112:115]
	v_mfma_f32_16x16x32_bf16 v[108:111], v[170:173], v[202:205], v[108:111]
	v_mfma_f32_16x16x32_bf16 v[96:99], v[132:135], v[210:213], v[96:99]
	v_mfma_f32_16x16x32_bf16 v[92:95], v[170:173], v[210:213], v[92:95]
	v_mfma_f32_16x16x32_bf16 v[80:83], v[132:135], v[218:221], v[80:83]
	v_mfma_f32_16x16x32_bf16 v[76:79], v[170:173], v[218:221], v[76:79]
	v_mfma_f32_16x16x32_bf16 v[128:131], v[136:139], v[198:201], v[128:131]
	v_mfma_f32_16x16x32_bf16 v[124:127], v[174:177], v[198:201], v[124:127]
	v_mfma_f32_16x16x32_bf16 v[112:115], v[136:139], v[206:209], v[112:115]
	v_mfma_f32_16x16x32_bf16 v[108:111], v[174:177], v[206:209], v[108:111]
	v_mfma_f32_16x16x32_bf16 v[96:99], v[136:139], v[214:217], v[96:99]
	v_mfma_f32_16x16x32_bf16 v[92:95], v[174:177], v[214:217], v[92:95]
	v_mfma_f32_16x16x32_bf16 v[80:83], v[136:139], v[222:225], v[80:83]
	v_mfma_f32_16x16x32_bf16 v[76:79], v[174:177], v[222:225], v[76:79]
	v_mfma_f32_16x16x32_bf16 v[120:123], v[178:181], v[194:197], v[120:123]
	v_mfma_f32_16x16x32_bf16 v[116:119], v[186:189], v[194:197], v[116:119]
	v_mfma_f32_16x16x32_bf16 v[104:107], v[178:181], v[202:205], v[104:107]
	v_mfma_f32_16x16x32_bf16 v[100:103], v[186:189], v[202:205], v[100:103]
	v_mfma_f32_16x16x32_bf16 v[88:91], v[178:181], v[210:213], v[88:91]
	v_mfma_f32_16x16x32_bf16 v[84:87], v[186:189], v[210:213], v[84:87]
	v_mfma_f32_16x16x32_bf16 v[72:75], v[178:181], v[218:221], v[72:75]
	v_mfma_f32_16x16x32_bf16 v[68:71], v[186:189], v[218:221], v[68:71]
	v_mfma_f32_16x16x32_bf16 v[120:123], v[182:185], v[198:201], v[120:123]
	v_mfma_f32_16x16x32_bf16 v[116:119], v[190:193], v[198:201], v[116:119]
	v_mfma_f32_16x16x32_bf16 v[104:107], v[182:185], v[206:209], v[104:107]
	v_mfma_f32_16x16x32_bf16 v[100:103], v[190:193], v[206:209], v[100:103]
	v_mfma_f32_16x16x32_bf16 v[88:91], v[182:185], v[214:217], v[88:91]
	v_mfma_f32_16x16x32_bf16 v[84:87], v[190:193], v[214:217], v[84:87]
	v_mfma_f32_16x16x32_bf16 v[72:75], v[182:185], v[222:225], v[72:75]
	v_mfma_f32_16x16x32_bf16 v[68:71], v[190:193], v[222:225], v[68:71]
	s_setprio 0
	s_barrier
	s_add_i32 s30, s54, s18
	v_lshl_add_u64 v[6:7], v[158:159], 0, s[24:25]
	s_mov_b32 m0, s30
	ds_read_b128 v[194:197], v165 offset:49152
	ds_read_b128 v[198:201], v165 offset:50176
	ds_read_b128 v[202:205], v165 offset:51200
	ds_read_b128 v[206:209], v165 offset:52224
	ds_read_b128 v[210:213], v165 offset:53248
	ds_read_b128 v[214:217], v165 offset:54272
	ds_read_b128 v[218:221], v165 offset:55296
	ds_read_b128 v[222:225], v165 offset:56320
	global_load_lds_dwordx4 v[6:7], off
	s_add_i32 m0, s30, 0x2000
	s_add_u32 s30, s52, 0xc0080
	v_lshl_add_u64 v[6:7], v[166:167], 0, s[24:25]
	s_addc_u32 s31, s53, 0
	s_add_i32 s52, s55, s18
	global_load_lds_dwordx4 v[6:7], off
	v_lshl_add_u64 v[6:7], s[30:31], 0, v[144:145]
	s_mov_b32 m0, s52
	s_nop 0
	global_load_lds_dwordx4 v[6:7], off
	v_lshl_add_u64 v[6:7], s[30:31], 0, v[140:141]
	s_add_i32 m0, s52, 0x2000
	s_nop 0
	global_load_lds_dwordx4 v[6:7], off
	v_lshl_add_u64 v[6:7], v[226:227], 0, s[24:25]
	s_mov_b32 m0, s73
	s_nop 0
	global_load_lds_dwordx4 v[6:7], off
	v_lshl_add_u64 v[6:7], v[228:229], 0, s[24:25]
	s_mov_b32 m0, s74
	s_nop 0
	global_load_lds_dwordx4 v[6:7], off
	s_waitcnt vmcnt(8)
	s_waitcnt lgkmcnt(0)
	s_barrier
	s_setprio 1
	s_waitcnt lgkmcnt(0)
	v_mfma_f32_16x16x32_bf16 v[64:67], v[132:135], v[194:197], v[64:67]
	v_mfma_f32_16x16x32_bf16 v[60:63], v[170:173], v[194:197], v[60:63]
	v_mfma_f32_16x16x32_bf16 v[48:51], v[132:135], v[202:205], v[48:51]
	v_mfma_f32_16x16x32_bf16 v[44:47], v[170:173], v[202:205], v[44:47]
	v_mfma_f32_16x16x32_bf16 v[32:35], v[132:135], v[210:213], v[32:35]
	v_mfma_f32_16x16x32_bf16 v[28:31], v[170:173], v[210:213], v[28:31]
	v_mfma_f32_16x16x32_bf16 v[16:19], v[132:135], v[218:221], v[16:19]
	v_mfma_f32_16x16x32_bf16 v[12:15], v[170:173], v[218:221], v[12:15]
	v_mfma_f32_16x16x32_bf16 v[64:67], v[136:139], v[198:201], v[64:67]
	v_mfma_f32_16x16x32_bf16 v[60:63], v[174:177], v[198:201], v[60:63]
	v_mfma_f32_16x16x32_bf16 v[48:51], v[136:139], v[206:209], v[48:51]
	v_mfma_f32_16x16x32_bf16 v[44:47], v[174:177], v[206:209], v[44:47]
	v_mfma_f32_16x16x32_bf16 v[32:35], v[136:139], v[214:217], v[32:35]
	v_mfma_f32_16x16x32_bf16 v[28:31], v[174:177], v[214:217], v[28:31]
	v_mfma_f32_16x16x32_bf16 v[16:19], v[136:139], v[222:225], v[16:19]
	v_mfma_f32_16x16x32_bf16 v[12:15], v[174:177], v[222:225], v[12:15]
	v_mfma_f32_16x16x32_bf16 v[56:59], v[178:181], v[194:197], v[56:59]
	v_mfma_f32_16x16x32_bf16 v[52:55], v[186:189], v[194:197], v[52:55]
	v_mfma_f32_16x16x32_bf16 v[40:43], v[178:181], v[202:205], v[40:43]
	v_mfma_f32_16x16x32_bf16 v[36:39], v[186:189], v[202:205], v[36:39]
	v_mfma_f32_16x16x32_bf16 v[24:27], v[178:181], v[210:213], v[24:27]
	v_mfma_f32_16x16x32_bf16 v[20:23], v[186:189], v[210:213], v[20:23]
	v_mfma_f32_16x16x32_bf16 v[6:9], v[178:181], v[218:221], v[8:11]
	v_mfma_f32_16x16x32_bf16 v[2:5], v[186:189], v[218:221], v[2:5]
	v_mfma_f32_16x16x32_bf16 v[56:59], v[182:185], v[198:201], v[56:59]
	v_mfma_f32_16x16x32_bf16 v[52:55], v[190:193], v[198:201], v[52:55]
	v_mfma_f32_16x16x32_bf16 v[40:43], v[182:185], v[206:209], v[40:43]
	v_mfma_f32_16x16x32_bf16 v[36:39], v[190:193], v[206:209], v[36:39]
	v_mfma_f32_16x16x32_bf16 v[24:27], v[182:185], v[214:217], v[24:27]
	v_mfma_f32_16x16x32_bf16 v[20:23], v[190:193], v[214:217], v[20:23]
	v_mfma_f32_16x16x32_bf16 v[8:11], v[182:185], v[222:225], v[6:9]
	v_mfma_f32_16x16x32_bf16 v[4:7], v[190:193], v[222:225], v[2:5]
	s_setprio 0
	s_barrier
	s_add_i32 s43, s43, 2
	s_add_u32 s50, s50, 0x100
	s_addc_u32 s51, s51, 0
	s_cmp_gt_u32 s43, 45
	s_cbranch_scc1 .LBB0_588

.LBB0_658:
	s_add_u32 s30, s12, s42
	s_addc_u32 s31, s13, s43
	s_add_u32 s30, s30, 0x100
	s_addc_u32 s31, s31, 0
	s_add_u32 s44, s65, s42
	s_addc_u32 s45, s68, s43
	s_add_i32 s74, 0, 0x10000
	s_cmpk_eq_i32 s42, 0xf00
	s_cselect_b32 s47, s17, s31
	s_cselect_b32 s46, s69, s30
	s_cselect_b32 s45, s15, s45
	s_cselect_b32 s44, s72, s44
	s_add_i32 s75, 0, 0x14000
	v_add_u32_e32 v160, s74, v135
	v_add_u32_e32 v174, s75, v135
	ds_read_b128 v[148:151], v160
	ds_read_b128 v[152:155], v160 offset:1024
	ds_read_b128 v[156:159], v160 offset:2048
	ds_read_b128 v[160:163], v160 offset:3072
	ds_read_b128 v[164:167], v174
	ds_read_b128 v[170:173], v174 offset:1024
	ds_read_b128 v[178:181], v174 offset:2048
	ds_read_b128 v[182:185], v174 offset:3072
	v_lshl_add_u64 v[174:175], v[144:145], 0, s[42:43]
	s_add_i32 m0, s52, 0xc000
	ds_read_b128 v[186:189], v147
	ds_read_b128 v[190:193], v147 offset:1024
	ds_read_b128 v[194:197], v147 offset:2048
	ds_read_b128 v[198:201], v147 offset:3072
	ds_read_b128 v[202:205], v147 offset:4096
	ds_read_b128 v[206:209], v147 offset:5120
	ds_read_b128 v[210:213], v147 offset:6144
	ds_read_b128 v[214:217], v147 offset:7168
	global_load_lds_dwordx4 v[174:175], off
	v_lshl_add_u64 v[174:175], v[142:143], 0, s[42:43]
	s_add_i32 m0, s52, 0xe000
	s_nop 0
	global_load_lds_dwordx4 v[174:175], off
	s_waitcnt vmcnt(8)
	s_waitcnt lgkmcnt(0)
	s_barrier
	s_setprio 1
	s_waitcnt lgkmcnt(0)
	v_mfma_f32_16x16x32_bf16 v[14:17], v[148:151], v[186:189], v[14:17]
	v_mfma_f32_16x16x32_bf16 v[10:13], v[156:159], v[186:189], v[10:13]
	v_mfma_f32_16x16x32_bf16 v[6:9], v[148:151], v[194:197], v[6:9]
	v_mfma_f32_16x16x32_bf16 v[2:5], v[156:159], v[194:197], v[2:5]
	v_mfma_f32_16x16x32_bf16 v[46:49], v[148:151], v[202:205], v[46:49]
	v_mfma_f32_16x16x32_bf16 v[42:45], v[156:159], v[202:205], v[42:45]
	v_mfma_f32_16x16x32_bf16 v[78:81], v[148:151], v[210:213], v[78:81]
	v_mfma_f32_16x16x32_bf16 v[74:77], v[156:159], v[210:213], v[74:77]
	v_mfma_f32_16x16x32_bf16 v[14:17], v[152:155], v[190:193], v[14:17]
	v_mfma_f32_16x16x32_bf16 v[10:13], v[160:163], v[190:193], v[10:13]
	v_mfma_f32_16x16x32_bf16 v[6:9], v[152:155], v[198:201], v[6:9]
	v_mfma_f32_16x16x32_bf16 v[2:5], v[160:163], v[198:201], v[2:5]
	v_mfma_f32_16x16x32_bf16 v[46:49], v[152:155], v[206:209], v[46:49]
	v_mfma_f32_16x16x32_bf16 v[42:45], v[160:163], v[206:209], v[42:45]
	v_mfma_f32_16x16x32_bf16 v[78:81], v[152:155], v[214:217], v[78:81]
	v_mfma_f32_16x16x32_bf16 v[74:77], v[160:163], v[214:217], v[74:77]
	v_mfma_f32_16x16x32_bf16 v[30:33], v[164:167], v[186:189], v[30:33]
	v_mfma_f32_16x16x32_bf16 v[26:29], v[178:181], v[186:189], v[26:29]
	v_mfma_f32_16x16x32_bf16 v[22:25], v[164:167], v[194:197], v[22:25]
	v_mfma_f32_16x16x32_bf16 v[18:21], v[178:181], v[194:197], v[18:21]
	v_mfma_f32_16x16x32_bf16 v[62:65], v[164:167], v[202:205], v[62:65]
	v_mfma_f32_16x16x32_bf16 v[58:61], v[178:181], v[202:205], v[58:61]
	v_mfma_f32_16x16x32_bf16 v[86:89], v[164:167], v[210:213], v[86:89]
	v_mfma_f32_16x16x32_bf16 v[82:85], v[178:181], v[210:213], v[82:85]
	v_mfma_f32_16x16x32_bf16 v[30:33], v[170:173], v[190:193], v[30:33]
	v_mfma_f32_16x16x32_bf16 v[26:29], v[182:185], v[190:193], v[26:29]
	v_mfma_f32_16x16x32_bf16 v[22:25], v[170:173], v[198:201], v[22:25]
	v_mfma_f32_16x16x32_bf16 v[18:21], v[182:185], v[198:201], v[18:21]
	v_mfma_f32_16x16x32_bf16 v[62:65], v[170:173], v[206:209], v[62:65]
	v_mfma_f32_16x16x32_bf16 v[58:61], v[182:185], v[206:209], v[58:61]
	v_mfma_f32_16x16x32_bf16 v[86:89], v[170:173], v[214:217], v[86:89]
	v_mfma_f32_16x16x32_bf16 v[82:85], v[182:185], v[214:217], v[82:85]
	s_setprio 0
	s_barrier
	s_add_i32 s30, s74, s29
	v_lshl_add_u64 v[174:175], s[44:45], 0, v[0:1]
	s_mov_b32 m0, s30
	ds_read_b128 v[186:189], v147 offset:16384
	ds_read_b128 v[190:193], v147 offset:17408
	ds_read_b128 v[194:197], v147 offset:18432
	ds_read_b128 v[198:201], v147 offset:19456
	ds_read_b128 v[202:205], v147 offset:20480
	ds_read_b128 v[206:209], v147 offset:21504
	ds_read_b128 v[210:213], v147 offset:22528
	ds_read_b128 v[214:217], v147 offset:23552
	global_load_lds_dwordx4 v[174:175], off
	s_add_i32 m0, s30, 0x2000
	s_add_u32 s30, s44, 0x80000
	v_lshl_add_u64 v[218:219], s[44:45], 0, v[130:131]
	s_addc_u32 s31, s45, 0
	s_add_i32 s74, s75, s29
	global_load_lds_dwordx4 v[218:219], off
	v_lshl_add_u64 v[220:221], s[30:31], 0, v[0:1]
	s_mov_b32 m0, s74
	v_lshl_add_u64 v[222:223], s[46:47], 0, v[132:133]
	global_load_lds_dwordx4 v[220:221], off
	v_lshl_add_u64 v[220:221], s[30:31], 0, v[130:131]
	s_add_i32 m0, s74, 0x2000
	s_nop 0
	global_load_lds_dwordx4 v[220:221], off
	v_lshl_add_u64 v[220:221], s[46:47], 0, v[136:137]
	s_mov_b32 m0, s52
	s_nop 0
	global_load_lds_dwordx4 v[220:221], off
	s_mov_b32 m0, s54
	s_nop 0
	global_load_lds_dwordx4 v[222:223], off
	s_waitcnt vmcnt(8)
	s_waitcnt lgkmcnt(0)
	s_barrier
	s_setprio 1
	s_waitcnt lgkmcnt(0)
	v_mfma_f32_16x16x32_bf16 v[102:105], v[148:151], v[186:189], v[102:105]
	v_mfma_f32_16x16x32_bf16 v[98:101], v[156:159], v[186:189], v[98:101]
	v_mfma_f32_16x16x32_bf16 v[126:129], v[148:151], v[194:197], v[126:129]
	v_mfma_f32_16x16x32_bf16 v[122:125], v[156:159], v[194:197], v[122:125]
	v_mfma_f32_16x16x32_bf16 v[94:97], v[148:151], v[202:205], v[94:97]
	v_mfma_f32_16x16x32_bf16 v[90:93], v[156:159], v[202:205], v[90:93]
	v_mfma_f32_16x16x32_bf16 v[54:57], v[148:151], v[210:213], v[54:57]
	v_mfma_f32_16x16x32_bf16 v[50:53], v[156:159], v[210:213], v[50:53]
	v_mfma_f32_16x16x32_bf16 v[102:105], v[152:155], v[190:193], v[102:105]
	v_mfma_f32_16x16x32_bf16 v[98:101], v[160:163], v[190:193], v[98:101]
	v_mfma_f32_16x16x32_bf16 v[126:129], v[152:155], v[198:201], v[126:129]
	v_mfma_f32_16x16x32_bf16 v[122:125], v[160:163], v[198:201], v[122:125]
	v_mfma_f32_16x16x32_bf16 v[94:97], v[152:155], v[206:209], v[94:97]
	v_mfma_f32_16x16x32_bf16 v[90:93], v[160:163], v[206:209], v[90:93]
	v_mfma_f32_16x16x32_bf16 v[54:57], v[152:155], v[214:217], v[54:57]
	v_mfma_f32_16x16x32_bf16 v[50:53], v[160:163], v[214:217], v[50:53]
	v_mfma_f32_16x16x32_bf16 v[118:121], v[164:167], v[186:189], v[118:121]
	v_mfma_f32_16x16x32_bf16 v[114:117], v[178:181], v[186:189], v[114:117]
	v_mfma_f32_16x16x32_bf16 v[110:113], v[164:167], v[194:197], v[110:113]
	v_mfma_f32_16x16x32_bf16 v[106:109], v[178:181], v[194:197], v[106:109]
	v_mfma_f32_16x16x32_bf16 v[70:73], v[164:167], v[202:205], v[70:73]
	v_mfma_f32_16x16x32_bf16 v[66:69], v[178:181], v[202:205], v[66:69]
	v_mfma_f32_16x16x32_bf16 v[38:41], v[164:167], v[210:213], v[38:41]
	v_mfma_f32_16x16x32_bf16 v[34:37], v[178:181], v[210:213], v[34:37]
	v_mfma_f32_16x16x32_bf16 v[118:121], v[170:173], v[190:193], v[118:121]
	v_mfma_f32_16x16x32_bf16 v[114:117], v[182:185], v[190:193], v[114:117]
	v_mfma_f32_16x16x32_bf16 v[110:113], v[170:173], v[198:201], v[110:113]
	v_mfma_f32_16x16x32_bf16 v[106:109], v[182:185], v[198:201], v[106:109]
	v_mfma_f32_16x16x32_bf16 v[70:73], v[170:173], v[206:209], v[70:73]
	v_mfma_f32_16x16x32_bf16 v[66:69], v[182:185], v[206:209], v[66:69]
	v_mfma_f32_16x16x32_bf16 v[38:41], v[170:173], v[214:217], v[38:41]
	v_mfma_f32_16x16x32_bf16 v[34:37], v[182:185], v[214:217], v[34:37]
	s_setprio 0
	s_barrier
	s_add_i32 s74, 0, 0x18000
	s_add_i32 s75, 0, 0x1c000
	v_add_u32_e32 v160, s74, v135
	v_add_u32_e32 v177, s75, v135
	ds_read_b128 v[148:151], v160
	ds_read_b128 v[152:155], v160 offset:1024
	ds_read_b128 v[156:159], v160 offset:2048
	ds_read_b128 v[160:163], v160 offset:3072
	ds_read_b128 v[164:167], v177
	ds_read_b128 v[170:173], v177 offset:1024
	ds_read_b128 v[178:181], v177 offset:2048
	ds_read_b128 v[182:185], v177 offset:3072
	s_add_u32 s30, s46, 0x80000
	s_addc_u32 s31, s47, 0
	s_mov_b32 m0, s55
	v_lshl_add_u64 v[224:225], s[30:31], 0, v[136:137]
	ds_read_b128 v[186:189], v147 offset:32768
	ds_read_b128 v[190:193], v147 offset:33792
	ds_read_b128 v[194:197], v147 offset:34816
	ds_read_b128 v[198:201], v147 offset:35840
	ds_read_b128 v[202:205], v147 offset:36864
	ds_read_b128 v[206:209], v147 offset:37888
	ds_read_b128 v[210:213], v147 offset:38912
	ds_read_b128 v[214:217], v147 offset:39936
	global_load_lds_dwordx4 v[224:225], off
	v_lshl_add_u64 v[224:225], s[30:31], 0, v[132:133]
	s_mov_b32 m0, s60
	s_nop 0
	global_load_lds_dwordx4 v[224:225], off
	s_waitcnt vmcnt(8)
	s_waitcnt lgkmcnt(0)
	s_barrier
	s_setprio 1
	s_waitcnt lgkmcnt(0)
	v_mfma_f32_16x16x32_bf16 v[14:17], v[148:151], v[186:189], v[14:17]
	v_mfma_f32_16x16x32_bf16 v[10:13], v[156:159], v[186:189], v[10:13]
	v_mfma_f32_16x16x32_bf16 v[6:9], v[148:151], v[194:197], v[6:9]
	v_mfma_f32_16x16x32_bf16 v[2:5], v[156:159], v[194:197], v[2:5]
	v_mfma_f32_16x16x32_bf16 v[46:49], v[148:151], v[202:205], v[46:49]
	v_mfma_f32_16x16x32_bf16 v[42:45], v[156:159], v[202:205], v[42:45]
	v_mfma_f32_16x16x32_bf16 v[78:81], v[148:151], v[210:213], v[78:81]
	v_mfma_f32_16x16x32_bf16 v[74:77], v[156:159], v[210:213], v[74:77]
	v_mfma_f32_16x16x32_bf16 v[14:17], v[152:155], v[190:193], v[14:17]
	v_mfma_f32_16x16x32_bf16 v[10:13], v[160:163], v[190:193], v[10:13]
	v_mfma_f32_16x16x32_bf16 v[6:9], v[152:155], v[198:201], v[6:9]
	v_mfma_f32_16x16x32_bf16 v[2:5], v[160:163], v[198:201], v[2:5]
	v_mfma_f32_16x16x32_bf16 v[46:49], v[152:155], v[206:209], v[46:49]
	v_mfma_f32_16x16x32_bf16 v[42:45], v[160:163], v[206:209], v[42:45]
	v_mfma_f32_16x16x32_bf16 v[78:81], v[152:155], v[214:217], v[78:81]
	v_mfma_f32_16x16x32_bf16 v[74:77], v[160:163], v[214:217], v[74:77]
	v_mfma_f32_16x16x32_bf16 v[30:33], v[164:167], v[186:189], v[30:33]
	v_mfma_f32_16x16x32_bf16 v[26:29], v[178:181], v[186:189], v[26:29]
	v_mfma_f32_16x16x32_bf16 v[22:25], v[164:167], v[194:197], v[22:25]
	v_mfma_f32_16x16x32_bf16 v[18:21], v[178:181], v[194:197], v[18:21]
	v_mfma_f32_16x16x32_bf16 v[62:65], v[164:167], v[202:205], v[62:65]
	v_mfma_f32_16x16x32_bf16 v[58:61], v[178:181], v[202:205], v[58:61]
	v_mfma_f32_16x16x32_bf16 v[86:89], v[164:167], v[210:213], v[86:89]
	v_mfma_f32_16x16x32_bf16 v[82:85], v[178:181], v[210:213], v[82:85]
	v_mfma_f32_16x16x32_bf16 v[30:33], v[170:173], v[190:193], v[30:33]
	v_mfma_f32_16x16x32_bf16 v[26:29], v[182:185], v[190:193], v[26:29]
	v_mfma_f32_16x16x32_bf16 v[22:25], v[170:173], v[198:201], v[22:25]
	v_mfma_f32_16x16x32_bf16 v[18:21], v[182:185], v[198:201], v[18:21]
	v_mfma_f32_16x16x32_bf16 v[62:65], v[170:173], v[206:209], v[62:65]
	v_mfma_f32_16x16x32_bf16 v[58:61], v[182:185], v[206:209], v[58:61]
	v_mfma_f32_16x16x32_bf16 v[86:89], v[170:173], v[214:217], v[86:89]
	v_mfma_f32_16x16x32_bf16 v[82:85], v[182:185], v[214:217], v[82:85]
	s_setprio 0
	s_barrier
	s_add_i32 s30, s74, s29
	v_lshl_add_u64 v[174:175], v[174:175], 0, s[24:25]
	s_mov_b32 m0, s30
	ds_read_b128 v[186:189], v147 offset:49152
	ds_read_b128 v[190:193], v147 offset:50176
	ds_read_b128 v[194:197], v147 offset:51200
	ds_read_b128 v[198:201], v147 offset:52224
	ds_read_b128 v[202:205], v147 offset:53248
	ds_read_b128 v[206:209], v147 offset:54272
	ds_read_b128 v[210:213], v147 offset:55296
	ds_read_b128 v[214:217], v147 offset:56320
	global_load_lds_dwordx4 v[174:175], off
	s_add_i32 m0, s30, 0x2000
	s_add_u32 s30, s44, 0x80080
	v_lshl_add_u64 v[174:175], v[218:219], 0, s[24:25]
	s_addc_u32 s31, s45, 0
	s_add_i32 s44, s75, s29
	global_load_lds_dwordx4 v[174:175], off
	v_lshl_add_u64 v[174:175], s[30:31], 0, v[0:1]
	s_mov_b32 m0, s44
	s_nop 0
	global_load_lds_dwordx4 v[174:175], off
	v_lshl_add_u64 v[174:175], s[30:31], 0, v[130:131]
	s_add_i32 m0, s44, 0x2000
	s_nop 0
	global_load_lds_dwordx4 v[174:175], off
	v_lshl_add_u64 v[174:175], v[220:221], 0, s[24:25]
	s_mov_b32 m0, s61
	s_nop 0
	global_load_lds_dwordx4 v[174:175], off
	v_lshl_add_u64 v[174:175], v[222:223], 0, s[24:25]
	s_mov_b32 m0, s62
	s_nop 0
	global_load_lds_dwordx4 v[174:175], off
	s_waitcnt vmcnt(8)
	s_waitcnt lgkmcnt(0)
	s_barrier
	s_setprio 1
	s_waitcnt lgkmcnt(0)
	v_mfma_f32_16x16x32_bf16 v[102:105], v[148:151], v[186:189], v[102:105]
	v_mfma_f32_16x16x32_bf16 v[98:101], v[156:159], v[186:189], v[98:101]
	v_mfma_f32_16x16x32_bf16 v[126:129], v[148:151], v[194:197], v[126:129]
	v_mfma_f32_16x16x32_bf16 v[122:125], v[156:159], v[194:197], v[122:125]
	v_mfma_f32_16x16x32_bf16 v[94:97], v[148:151], v[202:205], v[94:97]
	v_mfma_f32_16x16x32_bf16 v[90:93], v[156:159], v[202:205], v[90:93]
	v_mfma_f32_16x16x32_bf16 v[54:57], v[148:151], v[210:213], v[54:57]
	v_mfma_f32_16x16x32_bf16 v[50:53], v[156:159], v[210:213], v[50:53]
	v_mfma_f32_16x16x32_bf16 v[102:105], v[152:155], v[190:193], v[102:105]
	v_mfma_f32_16x16x32_bf16 v[98:101], v[160:163], v[190:193], v[98:101]
	v_mfma_f32_16x16x32_bf16 v[126:129], v[152:155], v[198:201], v[126:129]
	v_mfma_f32_16x16x32_bf16 v[122:125], v[160:163], v[198:201], v[122:125]
	v_mfma_f32_16x16x32_bf16 v[94:97], v[152:155], v[206:209], v[94:97]
	v_mfma_f32_16x16x32_bf16 v[90:93], v[160:163], v[206:209], v[90:93]
	v_mfma_f32_16x16x32_bf16 v[54:57], v[152:155], v[214:217], v[54:57]
	v_mfma_f32_16x16x32_bf16 v[50:53], v[160:163], v[214:217], v[50:53]
	v_mfma_f32_16x16x32_bf16 v[118:121], v[164:167], v[186:189], v[118:121]
	v_mfma_f32_16x16x32_bf16 v[114:117], v[178:181], v[186:189], v[114:117]
	v_mfma_f32_16x16x32_bf16 v[110:113], v[164:167], v[194:197], v[110:113]
	v_mfma_f32_16x16x32_bf16 v[106:109], v[178:181], v[194:197], v[106:109]
	v_mfma_f32_16x16x32_bf16 v[70:73], v[164:167], v[202:205], v[70:73]
	v_mfma_f32_16x16x32_bf16 v[66:69], v[178:181], v[202:205], v[66:69]
	v_mfma_f32_16x16x32_bf16 v[38:41], v[164:167], v[210:213], v[38:41]
	v_mfma_f32_16x16x32_bf16 v[34:37], v[178:181], v[210:213], v[34:37]
	v_mfma_f32_16x16x32_bf16 v[118:121], v[170:173], v[190:193], v[118:121]
	v_mfma_f32_16x16x32_bf16 v[114:117], v[182:185], v[190:193], v[114:117]
	v_mfma_f32_16x16x32_bf16 v[110:113], v[170:173], v[198:201], v[110:113]
	v_mfma_f32_16x16x32_bf16 v[106:109], v[182:185], v[198:201], v[106:109]
	v_mfma_f32_16x16x32_bf16 v[70:73], v[170:173], v[206:209], v[70:73]
	v_mfma_f32_16x16x32_bf16 v[66:69], v[182:185], v[206:209], v[66:69]
	v_mfma_f32_16x16x32_bf16 v[38:41], v[170:173], v[214:217], v[38:41]
	v_mfma_f32_16x16x32_bf16 v[34:37], v[182:185], v[214:217], v[34:37]
	s_setprio 0
	s_barrier
	s_add_i32 s73, s73, 2
	s_add_u32 s42, s42, 0x100
	s_addc_u32 s43, s43, 0
	s_cmp_gt_u32 s73, 29
	s_cbranch_scc0 .LBB0_658
	s_add_u32 s42, s65, 0xffffff00
	s_addc_u32 s43, s68, -1
	s_andn2_b64 vcc, exec, s[40:41]
	s_cbranch_vccnz .LBB0_649
	v_mov_b32_e32 v34, 0
	s_mov_b32 s0, s14
	s_mov_b32 s50, s16
	s_mov_b64 s[12:13], s[22:23]
	s_mov_b32 s63, s64
	v_mov_b32_e32 v35, v34
	v_mov_b32_e32 v36, v34
	v_mov_b32_e32 v37, v34
	v_mov_b32_e32 v38, v34
	v_mov_b32_e32 v39, v34
	v_mov_b32_e32 v40, v34
	v_mov_b32_e32 v41, v34
	v_mov_b32_e32 v66, v34
	v_mov_b32_e32 v67, v34
	v_mov_b32_e32 v68, v34
	v_mov_b32_e32 v69, v34
	v_mov_b32_e32 v70, v34
	v_mov_b32_e32 v71, v34
	v_mov_b32_e32 v72, v34
	v_mov_b32_e32 v73, v34
	v_mov_b32_e32 v106, v34
	v_mov_b32_e32 v107, v34
	v_mov_b32_e32 v108, v34
	v_mov_b32_e32 v109, v34
	v_mov_b32_e32 v110, v34
	v_mov_b32_e32 v111, v34
	v_mov_b32_e32 v112, v34
	v_mov_b32_e32 v113, v34
	v_mov_b32_e32 v114, v34
	v_mov_b32_e32 v115, v34
	v_mov_b32_e32 v116, v34
	v_mov_b32_e32 v117, v34
	v_mov_b32_e32 v118, v34
	v_mov_b32_e32 v119, v34
	v_mov_b32_e32 v120, v34
	v_mov_b32_e32 v121, v34
	v_mov_b32_e32 v50, v34
	v_mov_b32_e32 v51, v34
	v_mov_b32_e32 v52, v34
	v_mov_b32_e32 v53, v34
	v_mov_b32_e32 v54, v34
	v_mov_b32_e32 v55, v34
	v_mov_b32_e32 v56, v34
	v_mov_b32_e32 v57, v34
	v_mov_b32_e32 v90, v34
	v_mov_b32_e32 v91, v34
	v_mov_b32_e32 v92, v34
	v_mov_b32_e32 v93, v34
	v_mov_b32_e32 v94, v34
	v_mov_b32_e32 v95, v34
	v_mov_b32_e32 v96, v34
	v_mov_b32_e32 v97, v34
	v_mov_b32_e32 v122, v34
	v_mov_b32_e32 v123, v34
	v_mov_b32_e32 v124, v34
	v_mov_b32_e32 v125, v34
	v_mov_b32_e32 v126, v34
	v_mov_b32_e32 v127, v34
	v_mov_b32_e32 v128, v34
	v_mov_b32_e32 v129, v34
	v_mov_b32_e32 v98, v34
	v_mov_b32_e32 v99, v34
	v_mov_b32_e32 v100, v34
	v_mov_b32_e32 v101, v34
	v_mov_b32_e32 v102, v34
	v_mov_b32_e32 v103, v34
	v_mov_b32_e32 v104, v34
	v_mov_b32_e32 v105, v34
	v_mov_b32_e32 v82, v34
	v_mov_b32_e32 v83, v34
	v_mov_b32_e32 v84, v34
	v_mov_b32_e32 v85, v34
	v_mov_b32_e32 v86, v34
	v_mov_b32_e32 v87, v34
	v_mov_b32_e32 v88, v34
	v_mov_b32_e32 v89, v34
	v_mov_b32_e32 v58, v34
	v_mov_b32_e32 v59, v34
	v_mov_b32_e32 v60, v34
	v_mov_b32_e32 v61, v34
	v_mov_b32_e32 v62, v34
	v_mov_b32_e32 v63, v34
	v_mov_b32_e32 v64, v34
	v_mov_b32_e32 v65, v34
	v_mov_b32_e32 v18, v34
	v_mov_b32_e32 v19, v34
	v_mov_b32_e32 v20, v34
	v_mov_b32_e32 v21, v34
	v_mov_b32_e32 v22, v34
	v_mov_b32_e32 v23, v34
	v_mov_b32_e32 v24, v34
	v_mov_b32_e32 v25, v34
	v_mov_b32_e32 v26, v34
	v_mov_b32_e32 v27, v34
	v_mov_b32_e32 v28, v34
	v_mov_b32_e32 v29, v34
	v_mov_b32_e32 v30, v34
	v_mov_b32_e32 v31, v34
	v_mov_b32_e32 v32, v34
	v_mov_b32_e32 v33, v34
	v_mov_b32_e32 v74, v34
	v_mov_b32_e32 v75, v34
	v_mov_b32_e32 v76, v34
	v_mov_b32_e32 v77, v34
	v_mov_b32_e32 v78, v34
	v_mov_b32_e32 v79, v34
	v_mov_b32_e32 v80, v34
	v_mov_b32_e32 v81, v34
	v_mov_b32_e32 v42, v34
	v_mov_b32_e32 v43, v34
	v_mov_b32_e32 v44, v34
	v_mov_b32_e32 v45, v34
	v_mov_b32_e32 v46, v34
	v_mov_b32_e32 v47, v34
	v_mov_b32_e32 v48, v34
	v_mov_b32_e32 v49, v34
	v_mov_b32_e32 v2, v34
	v_mov_b32_e32 v3, v34
	v_mov_b32_e32 v4, v34
	v_mov_b32_e32 v5, v34
	v_mov_b32_e32 v6, v34
	v_mov_b32_e32 v7, v34
	v_mov_b32_e32 v8, v34
	v_mov_b32_e32 v9, v34
	v_mov_b32_e32 v10, v34
	v_mov_b32_e32 v11, v34
	v_mov_b32_e32 v12, v34
	v_mov_b32_e32 v13, v34
	v_mov_b32_e32 v14, v34
	v_mov_b32_e32 v15, v34
	v_mov_b32_e32 v16, v34
	v_mov_b32_e32 v17, v34
	s_andn2_b64 vcc, exec, s[38:39]
	s_cbranch_vccnz .LBB0_650

.LBB0_764:
	s_add_u32 s64, s62, 0x100
	s_addc_u32 s65, s63, 0
	s_add_i32 s30, 0, 0x10000
	s_cmp_eq_u32 s81, 28
	s_cselect_b32 s75, s51, s65
	s_cselect_b32 s74, s77, s64
	s_cselect_b32 s73, s49, s80
	s_cselect_b32 s72, s78, s79
	s_add_i32 s82, 0, 0x14000
	v_add_u32_e32 v142, s30, v220
	v_add_u32_e32 v158, s82, v220
	ds_read_b128 v[130:133], v142
	ds_read_b128 v[134:137], v142 offset:1024
	ds_read_b128 v[138:141], v142 offset:2048
	ds_read_b128 v[142:145], v142 offset:3072
	ds_read_b128 v[146:149], v158
	ds_read_b128 v[150:153], v158 offset:1024
	ds_read_b128 v[154:157], v158 offset:2048
	ds_read_b128 v[158:161], v158 offset:3072
	v_lshl_add_u64 v[166:167], s[62:63], 0, v[182:183]
	s_add_i32 m0, s9, 0xc000
	ds_read_b128 v[162:165], v222
	ds_read_b128 v[170:173], v222 offset:1024
	ds_read_b128 v[184:187], v222 offset:2048
	ds_read_b128 v[188:191], v222 offset:3072
	ds_read_b128 v[192:195], v222 offset:4096
	ds_read_b128 v[196:199], v222 offset:5120
	ds_read_b128 v[200:203], v222 offset:6144
	ds_read_b128 v[204:207], v222 offset:7168
	global_load_lds_dwordx4 v[166:167], off
	v_lshl_add_u64 v[166:167], s[62:63], 0, v[180:181]
	s_add_i32 m0, s9, 0xe000
	s_nop 0
	global_load_lds_dwordx4 v[166:167], off
	s_waitcnt vmcnt(8)
	s_waitcnt lgkmcnt(0)
	s_barrier
	s_setprio 1
	s_waitcnt lgkmcnt(0)
	v_mfma_f32_16x16x32_bf16 v[94:97], v[130:133], v[162:165], v[94:97]
	v_mfma_f32_16x16x32_bf16 v[126:129], v[138:141], v[162:165], v[126:129]
	v_mfma_f32_16x16x32_bf16 v[90:93], v[130:133], v[184:187], v[90:93]
	v_mfma_f32_16x16x32_bf16 v[122:125], v[138:141], v[184:187], v[122:125]
	v_mfma_f32_16x16x32_bf16 v[86:89], v[130:133], v[192:195], v[86:89]
	v_mfma_f32_16x16x32_bf16 v[118:121], v[138:141], v[192:195], v[118:121]
	v_mfma_f32_16x16x32_bf16 v[82:85], v[130:133], v[200:203], v[82:85]
	v_mfma_f32_16x16x32_bf16 v[114:117], v[138:141], v[200:203], v[114:117]
	v_mfma_f32_16x16x32_bf16 v[94:97], v[134:137], v[170:173], v[94:97]
	v_mfma_f32_16x16x32_bf16 v[126:129], v[142:145], v[170:173], v[126:129]
	v_mfma_f32_16x16x32_bf16 v[90:93], v[134:137], v[188:191], v[90:93]
	v_mfma_f32_16x16x32_bf16 v[122:125], v[142:145], v[188:191], v[122:125]
	v_mfma_f32_16x16x32_bf16 v[86:89], v[134:137], v[196:199], v[86:89]
	v_mfma_f32_16x16x32_bf16 v[118:121], v[142:145], v[196:199], v[118:121]
	v_mfma_f32_16x16x32_bf16 v[82:85], v[134:137], v[204:207], v[82:85]
	v_mfma_f32_16x16x32_bf16 v[114:117], v[142:145], v[204:207], v[114:117]
	v_mfma_f32_16x16x32_bf16 v[78:81], v[146:149], v[162:165], v[78:81]
	v_mfma_f32_16x16x32_bf16 v[110:113], v[154:157], v[162:165], v[110:113]
	v_mfma_f32_16x16x32_bf16 v[74:77], v[146:149], v[184:187], v[74:77]
	v_mfma_f32_16x16x32_bf16 v[106:109], v[154:157], v[184:187], v[106:109]
	v_mfma_f32_16x16x32_bf16 v[70:73], v[146:149], v[192:195], v[70:73]
	v_mfma_f32_16x16x32_bf16 v[102:105], v[154:157], v[192:195], v[102:105]
	v_mfma_f32_16x16x32_bf16 v[66:69], v[146:149], v[200:203], v[66:69]
	v_mfma_f32_16x16x32_bf16 v[98:101], v[154:157], v[200:203], v[98:101]
	v_mfma_f32_16x16x32_bf16 v[78:81], v[150:153], v[170:173], v[78:81]
	v_mfma_f32_16x16x32_bf16 v[110:113], v[158:161], v[170:173], v[110:113]
	v_mfma_f32_16x16x32_bf16 v[74:77], v[150:153], v[188:191], v[74:77]
	v_mfma_f32_16x16x32_bf16 v[106:109], v[158:161], v[188:191], v[106:109]
	v_mfma_f32_16x16x32_bf16 v[70:73], v[150:153], v[196:199], v[70:73]
	v_mfma_f32_16x16x32_bf16 v[102:105], v[158:161], v[196:199], v[102:105]
	v_mfma_f32_16x16x32_bf16 v[66:69], v[150:153], v[204:207], v[66:69]
	v_mfma_f32_16x16x32_bf16 v[98:101], v[158:161], v[204:207], v[98:101]
	s_setprio 0
	s_barrier
	s_add_i32 s30, s30, s8
	v_lshl_add_u64 v[166:167], s[72:73], 0, v[0:1]
	s_mov_b32 m0, s30
	ds_read_b128 v[162:165], v222 offset:16384
	ds_read_b128 v[170:173], v222 offset:17408
	ds_read_b128 v[184:187], v222 offset:18432
	ds_read_b128 v[188:191], v222 offset:19456
	ds_read_b128 v[192:195], v222 offset:20480
	ds_read_b128 v[196:199], v222 offset:21504
	ds_read_b128 v[200:203], v222 offset:22528
	ds_read_b128 v[204:207], v222 offset:23552
	global_load_lds_dwordx4 v[166:167], off
	s_add_i32 m0, s30, 0x2000
	s_add_u32 s30, s72, 0x80000
	v_lshl_add_u64 v[208:209], s[72:73], 0, v[174:175]
	s_addc_u32 s31, s73, 0
	s_add_i32 s62, s82, s8
	global_load_lds_dwordx4 v[208:209], off
	v_lshl_add_u64 v[210:211], s[30:31], 0, v[0:1]
	s_mov_b32 m0, s62
	v_lshl_add_u64 v[212:213], s[74:75], 0, v[176:177]
	global_load_lds_dwordx4 v[210:211], off
	v_lshl_add_u64 v[210:211], s[30:31], 0, v[174:175]
	s_add_i32 m0, s62, 0x2000
	s_nop 0
	global_load_lds_dwordx4 v[210:211], off
	v_lshl_add_u64 v[210:211], s[74:75], 0, v[178:179]
	s_mov_b32 m0, s9
	s_nop 0
	global_load_lds_dwordx4 v[210:211], off
	s_mov_b32 m0, s18
	s_nop 0
	global_load_lds_dwordx4 v[212:213], off
	s_waitcnt vmcnt(8)
	s_waitcnt lgkmcnt(0)
	s_barrier
	s_setprio 1
	s_waitcnt lgkmcnt(0)
	v_mfma_f32_16x16x32_bf16 v[10:13], v[130:133], v[162:165], v[10:13]
	v_mfma_f32_16x16x32_bf16 v[42:45], v[138:141], v[162:165], v[42:45]
	v_mfma_f32_16x16x32_bf16 v[18:21], v[130:133], v[184:187], v[18:21]
	v_mfma_f32_16x16x32_bf16 v[50:53], v[138:141], v[184:187], v[50:53]
	v_mfma_f32_16x16x32_bf16 v[26:29], v[130:133], v[192:195], v[26:29]
	v_mfma_f32_16x16x32_bf16 v[58:61], v[138:141], v[192:195], v[58:61]
	v_mfma_f32_16x16x32_bf16 v[30:33], v[130:133], v[200:203], v[30:33]
	v_mfma_f32_16x16x32_bf16 v[62:65], v[138:141], v[200:203], v[62:65]
	v_mfma_f32_16x16x32_bf16 v[10:13], v[134:137], v[170:173], v[10:13]
	v_mfma_f32_16x16x32_bf16 v[42:45], v[142:145], v[170:173], v[42:45]
	v_mfma_f32_16x16x32_bf16 v[18:21], v[134:137], v[188:191], v[18:21]
	v_mfma_f32_16x16x32_bf16 v[50:53], v[142:145], v[188:191], v[50:53]
	v_mfma_f32_16x16x32_bf16 v[26:29], v[134:137], v[196:199], v[26:29]
	v_mfma_f32_16x16x32_bf16 v[58:61], v[142:145], v[196:199], v[58:61]
	v_mfma_f32_16x16x32_bf16 v[30:33], v[134:137], v[204:207], v[30:33]
	v_mfma_f32_16x16x32_bf16 v[62:65], v[142:145], v[204:207], v[62:65]
	v_mfma_f32_16x16x32_bf16 v[2:5], v[146:149], v[162:165], v[2:5]
	v_mfma_f32_16x16x32_bf16 v[34:37], v[154:157], v[162:165], v[34:37]
	v_mfma_f32_16x16x32_bf16 v[6:9], v[146:149], v[184:187], v[6:9]
	v_mfma_f32_16x16x32_bf16 v[38:41], v[154:157], v[184:187], v[38:41]
	v_mfma_f32_16x16x32_bf16 v[14:17], v[146:149], v[192:195], v[14:17]
	v_mfma_f32_16x16x32_bf16 v[46:49], v[154:157], v[192:195], v[46:49]
	v_mfma_f32_16x16x32_bf16 v[22:25], v[146:149], v[200:203], v[22:25]
	v_mfma_f32_16x16x32_bf16 v[54:57], v[154:157], v[200:203], v[54:57]
	v_mfma_f32_16x16x32_bf16 v[2:5], v[150:153], v[170:173], v[2:5]
	v_mfma_f32_16x16x32_bf16 v[34:37], v[158:161], v[170:173], v[34:37]
	v_mfma_f32_16x16x32_bf16 v[6:9], v[150:153], v[188:191], v[6:9]
	v_mfma_f32_16x16x32_bf16 v[38:41], v[158:161], v[188:191], v[38:41]
	v_mfma_f32_16x16x32_bf16 v[14:17], v[150:153], v[196:199], v[14:17]
	v_mfma_f32_16x16x32_bf16 v[46:49], v[158:161], v[196:199], v[46:49]
	v_mfma_f32_16x16x32_bf16 v[22:25], v[150:153], v[204:207], v[22:25]
	v_mfma_f32_16x16x32_bf16 v[54:57], v[158:161], v[204:207], v[54:57]
	s_setprio 0
	s_barrier
	s_add_i32 s62, 0, 0x18000
	s_add_i32 s63, 0, 0x1c000
	v_add_u32_e32 v142, s62, v220
	v_add_u32_e32 v158, s63, v220
	ds_read_b128 v[130:133], v142
	ds_read_b128 v[134:137], v142 offset:1024
	ds_read_b128 v[138:141], v142 offset:2048
	ds_read_b128 v[142:145], v142 offset:3072
	ds_read_b128 v[146:149], v158
	ds_read_b128 v[150:153], v158 offset:1024
	ds_read_b128 v[154:157], v158 offset:2048
	ds_read_b128 v[158:161], v158 offset:3072
	s_add_u32 s30, s74, 0x80000
	s_addc_u32 s31, s75, 0
	s_mov_b32 m0, s28
	v_lshl_add_u64 v[214:215], s[30:31], 0, v[178:179]
	ds_read_b128 v[162:165], v222 offset:32768
	ds_read_b128 v[170:173], v222 offset:33792
	ds_read_b128 v[184:187], v222 offset:34816
	ds_read_b128 v[188:191], v222 offset:35840
	ds_read_b128 v[192:195], v222 offset:36864
	ds_read_b128 v[196:199], v222 offset:37888
	ds_read_b128 v[200:203], v222 offset:38912
	ds_read_b128 v[204:207], v222 offset:39936
	global_load_lds_dwordx4 v[214:215], off
	v_lshl_add_u64 v[214:215], s[30:31], 0, v[176:177]
	s_mov_b32 m0, s29
	s_nop 0
	global_load_lds_dwordx4 v[214:215], off
	s_waitcnt vmcnt(8)
	s_waitcnt lgkmcnt(0)
	s_barrier
	s_setprio 1
	s_waitcnt lgkmcnt(0)
	v_mfma_f32_16x16x32_bf16 v[94:97], v[130:133], v[162:165], v[94:97]
	v_mfma_f32_16x16x32_bf16 v[126:129], v[138:141], v[162:165], v[126:129]
	v_mfma_f32_16x16x32_bf16 v[90:93], v[130:133], v[184:187], v[90:93]
	v_mfma_f32_16x16x32_bf16 v[122:125], v[138:141], v[184:187], v[122:125]
	v_mfma_f32_16x16x32_bf16 v[86:89], v[130:133], v[192:195], v[86:89]
	v_mfma_f32_16x16x32_bf16 v[118:121], v[138:141], v[192:195], v[118:121]
	v_mfma_f32_16x16x32_bf16 v[82:85], v[130:133], v[200:203], v[82:85]
	v_mfma_f32_16x16x32_bf16 v[114:117], v[138:141], v[200:203], v[114:117]
	v_mfma_f32_16x16x32_bf16 v[94:97], v[134:137], v[170:173], v[94:97]
	v_mfma_f32_16x16x32_bf16 v[126:129], v[142:145], v[170:173], v[126:129]
	v_mfma_f32_16x16x32_bf16 v[90:93], v[134:137], v[188:191], v[90:93]
	v_mfma_f32_16x16x32_bf16 v[122:125], v[142:145], v[188:191], v[122:125]
	v_mfma_f32_16x16x32_bf16 v[86:89], v[134:137], v[196:199], v[86:89]
	v_mfma_f32_16x16x32_bf16 v[118:121], v[142:145], v[196:199], v[118:121]
	v_mfma_f32_16x16x32_bf16 v[82:85], v[134:137], v[204:207], v[82:85]
	v_mfma_f32_16x16x32_bf16 v[114:117], v[142:145], v[204:207], v[114:117]
	v_mfma_f32_16x16x32_bf16 v[78:81], v[146:149], v[162:165], v[78:81]
	v_mfma_f32_16x16x32_bf16 v[110:113], v[154:157], v[162:165], v[110:113]
	v_mfma_f32_16x16x32_bf16 v[74:77], v[146:149], v[184:187], v[74:77]
	v_mfma_f32_16x16x32_bf16 v[106:109], v[154:157], v[184:187], v[106:109]
	v_mfma_f32_16x16x32_bf16 v[70:73], v[146:149], v[192:195], v[70:73]
	v_mfma_f32_16x16x32_bf16 v[102:105], v[154:157], v[192:195], v[102:105]
	v_mfma_f32_16x16x32_bf16 v[66:69], v[146:149], v[200:203], v[66:69]
	v_mfma_f32_16x16x32_bf16 v[98:101], v[154:157], v[200:203], v[98:101]
	v_mfma_f32_16x16x32_bf16 v[78:81], v[150:153], v[170:173], v[78:81]
	v_mfma_f32_16x16x32_bf16 v[110:113], v[158:161], v[170:173], v[110:113]
	v_mfma_f32_16x16x32_bf16 v[74:77], v[150:153], v[188:191], v[74:77]
	v_mfma_f32_16x16x32_bf16 v[106:109], v[158:161], v[188:191], v[106:109]
	v_mfma_f32_16x16x32_bf16 v[70:73], v[150:153], v[196:199], v[70:73]
	v_mfma_f32_16x16x32_bf16 v[102:105], v[158:161], v[196:199], v[102:105]
	v_mfma_f32_16x16x32_bf16 v[66:69], v[150:153], v[204:207], v[66:69]
	v_mfma_f32_16x16x32_bf16 v[98:101], v[158:161], v[204:207], v[98:101]
	s_setprio 0
	s_barrier
	s_add_i32 s30, s62, s8
	v_lshl_add_u64 v[166:167], v[166:167], 0, s[24:25]
	s_mov_b32 m0, s30
	ds_read_b128 v[162:165], v222 offset:49152
	ds_read_b128 v[170:173], v222 offset:50176
	ds_read_b128 v[184:187], v222 offset:51200
	ds_read_b128 v[188:191], v222 offset:52224
	ds_read_b128 v[192:195], v222 offset:53248
	ds_read_b128 v[196:199], v222 offset:54272
	ds_read_b128 v[200:203], v222 offset:55296
	ds_read_b128 v[204:207], v222 offset:56320
	global_load_lds_dwordx4 v[166:167], off
	s_add_i32 m0, s30, 0x2000
	s_add_u32 s30, s72, 0x80080
	v_lshl_add_u64 v[166:167], v[208:209], 0, s[24:25]
	s_addc_u32 s31, s73, 0
	s_add_i32 s62, s63, s8
	global_load_lds_dwordx4 v[166:167], off
	v_lshl_add_u64 v[166:167], s[30:31], 0, v[0:1]
	s_mov_b32 m0, s62
	s_nop 0
	global_load_lds_dwordx4 v[166:167], off
	v_lshl_add_u64 v[166:167], s[30:31], 0, v[174:175]
	s_add_i32 m0, s62, 0x2000
	s_nop 0
	global_load_lds_dwordx4 v[166:167], off
	v_lshl_add_u64 v[166:167], v[210:211], 0, s[24:25]
	s_mov_b32 m0, s54
	s_nop 0
	global_load_lds_dwordx4 v[166:167], off
	v_lshl_add_u64 v[166:167], v[212:213], 0, s[24:25]
	s_mov_b32 m0, s55
	s_nop 0
	global_load_lds_dwordx4 v[166:167], off
	s_waitcnt vmcnt(8)
	s_waitcnt lgkmcnt(0)
	s_barrier
	s_setprio 1
	s_waitcnt lgkmcnt(0)
	v_mfma_f32_16x16x32_bf16 v[10:13], v[130:133], v[162:165], v[10:13]
	v_mfma_f32_16x16x32_bf16 v[42:45], v[138:141], v[162:165], v[42:45]
	v_mfma_f32_16x16x32_bf16 v[18:21], v[130:133], v[184:187], v[18:21]
	v_mfma_f32_16x16x32_bf16 v[50:53], v[138:141], v[184:187], v[50:53]
	v_mfma_f32_16x16x32_bf16 v[26:29], v[130:133], v[192:195], v[26:29]
	v_mfma_f32_16x16x32_bf16 v[58:61], v[138:141], v[192:195], v[58:61]
	v_mfma_f32_16x16x32_bf16 v[30:33], v[130:133], v[200:203], v[30:33]
	v_mfma_f32_16x16x32_bf16 v[62:65], v[138:141], v[200:203], v[62:65]
	v_mfma_f32_16x16x32_bf16 v[10:13], v[134:137], v[170:173], v[10:13]
	v_mfma_f32_16x16x32_bf16 v[42:45], v[142:145], v[170:173], v[42:45]
	v_mfma_f32_16x16x32_bf16 v[18:21], v[134:137], v[188:191], v[18:21]
	v_mfma_f32_16x16x32_bf16 v[50:53], v[142:145], v[188:191], v[50:53]
	v_mfma_f32_16x16x32_bf16 v[26:29], v[134:137], v[196:199], v[26:29]
	v_mfma_f32_16x16x32_bf16 v[58:61], v[142:145], v[196:199], v[58:61]
	v_mfma_f32_16x16x32_bf16 v[30:33], v[134:137], v[204:207], v[30:33]
	v_mfma_f32_16x16x32_bf16 v[62:65], v[142:145], v[204:207], v[62:65]
	v_mfma_f32_16x16x32_bf16 v[2:5], v[146:149], v[162:165], v[2:5]
	v_mfma_f32_16x16x32_bf16 v[34:37], v[154:157], v[162:165], v[34:37]
	v_mfma_f32_16x16x32_bf16 v[6:9], v[146:149], v[184:187], v[6:9]
	v_mfma_f32_16x16x32_bf16 v[38:41], v[154:157], v[184:187], v[38:41]
	v_mfma_f32_16x16x32_bf16 v[14:17], v[146:149], v[192:195], v[14:17]
	v_mfma_f32_16x16x32_bf16 v[46:49], v[154:157], v[192:195], v[46:49]
	v_mfma_f32_16x16x32_bf16 v[22:25], v[146:149], v[200:203], v[22:25]
	v_mfma_f32_16x16x32_bf16 v[54:57], v[154:157], v[200:203], v[54:57]
	v_mfma_f32_16x16x32_bf16 v[2:5], v[150:153], v[170:173], v[2:5]
	v_mfma_f32_16x16x32_bf16 v[34:37], v[158:161], v[170:173], v[34:37]
	v_mfma_f32_16x16x32_bf16 v[6:9], v[150:153], v[188:191], v[6:9]
	v_mfma_f32_16x16x32_bf16 v[38:41], v[158:161], v[188:191], v[38:41]
	v_mfma_f32_16x16x32_bf16 v[14:17], v[150:153], v[196:199], v[14:17]
	v_mfma_f32_16x16x32_bf16 v[46:49], v[158:161], v[196:199], v[46:49]
	v_mfma_f32_16x16x32_bf16 v[22:25], v[150:153], v[204:207], v[22:25]
	v_mfma_f32_16x16x32_bf16 v[54:57], v[158:161], v[204:207], v[54:57]
	s_setprio 0
	s_barrier
	s_add_i32 s81, s81, 2
	s_add_u32 s79, s79, 0x100
	s_addc_u32 s80, s80, 0
	s_cmp_gt_u32 s81, 29
	s_mov_b64 s[62:63], s[64:65]
	s_cbranch_scc0 .LBB0_764
	s_and_b64 vcc, exec, s[42:43]
	s_cbranch_vccz .LBB0_767
	s_barrier

.LBB0_966:
	s_add_u32 s30, s20, s40
	s_addc_u32 s31, s21, s41
	s_add_u32 s30, s30, 0x100
	s_addc_u32 s31, s31, 0
	s_add_u32 s42, s62, s40
	s_addc_u32 s43, s63, s41
	s_add_i32 s65, 0, 0x10000
	s_cmpk_eq_i32 s40, 0x2b00
	s_cselect_b32 s45, s23, s31
	s_cselect_b32 s44, s22, s30
	v_add_u32_e32 v147, s65, v145
	s_cselect_b32 s43, s1, s43
	s_cselect_b32 s42, s0, s42
	s_add_i32 s68, 0, 0x14000
	ds_read_b128 v[148:151], v147
	ds_read_b128 v[152:155], v147 offset:1024
	ds_read_b128 v[156:159], v147 offset:2048
	ds_read_b128 v[160:163], v147 offset:3072
	v_add_u32_e32 v147, s68, v145
	ds_read_b128 v[170:173], v147
	ds_read_b128 v[174:177], v147 offset:1024
	ds_read_b128 v[178:181], v147 offset:2048
	ds_read_b128 v[182:185], v147 offset:3072
	v_lshl_add_u64 v[166:167], v[142:143], 0, s[40:41]
	s_add_i32 m0, s28, 0xc000
	ds_read_b128 v[186:189], v146
	ds_read_b128 v[190:193], v146 offset:1024
	ds_read_b128 v[194:197], v146 offset:2048
	ds_read_b128 v[200:203], v146 offset:3072
	ds_read_b128 v[204:207], v146 offset:4096
	ds_read_b128 v[208:211], v146 offset:5120
	ds_read_b128 v[212:215], v146 offset:6144
	ds_read_b128 v[216:219], v146 offset:7168
	global_load_lds_dwordx4 v[166:167], off
	v_lshl_add_u64 v[166:167], v[140:141], 0, s[40:41]
	s_add_i32 m0, s28, 0xe000
	s_nop 0
	global_load_lds_dwordx4 v[166:167], off
	s_waitcnt vmcnt(8)
	s_waitcnt lgkmcnt(0)
	s_barrier
	s_setprio 1
	s_waitcnt lgkmcnt(0)
	v_mfma_f32_16x16x32_bf16 v[128:131], v[148:151], v[186:189], v[128:131]
	v_mfma_f32_16x16x32_bf16 v[124:127], v[156:159], v[186:189], v[124:127]
	v_mfma_f32_16x16x32_bf16 v[120:123], v[148:151], v[194:197], v[120:123]
	v_mfma_f32_16x16x32_bf16 v[116:119], v[156:159], v[194:197], v[116:119]
	v_mfma_f32_16x16x32_bf16 v[108:111], v[148:151], v[204:207], v[108:111]
	v_mfma_f32_16x16x32_bf16 v[104:107], v[156:159], v[204:207], v[104:107]
	v_mfma_f32_16x16x32_bf16 v[100:103], v[148:151], v[212:215], v[100:103]
	v_mfma_f32_16x16x32_bf16 v[92:95], v[156:159], v[212:215], v[92:95]
	v_mfma_f32_16x16x32_bf16 v[128:131], v[152:155], v[190:193], v[128:131]
	v_mfma_f32_16x16x32_bf16 v[124:127], v[160:163], v[190:193], v[124:127]
	v_mfma_f32_16x16x32_bf16 v[120:123], v[152:155], v[200:203], v[120:123]
	v_mfma_f32_16x16x32_bf16 v[116:119], v[160:163], v[200:203], v[116:119]
	v_mfma_f32_16x16x32_bf16 v[108:111], v[152:155], v[208:211], v[108:111]
	v_mfma_f32_16x16x32_bf16 v[104:107], v[160:163], v[208:211], v[104:107]
	v_mfma_f32_16x16x32_bf16 v[100:103], v[152:155], v[216:219], v[100:103]
	v_mfma_f32_16x16x32_bf16 v[92:95], v[160:163], v[216:219], v[92:95]
	v_mfma_f32_16x16x32_bf16 v[112:115], v[170:173], v[186:189], v[112:115]
	v_mfma_f32_16x16x32_bf16 v[96:99], v[178:181], v[186:189], v[96:99]
	v_mfma_f32_16x16x32_bf16 v[76:79], v[170:173], v[194:197], v[76:79]
	v_mfma_f32_16x16x32_bf16 v[64:67], v[178:181], v[194:197], v[64:67]
	v_mfma_f32_16x16x32_bf16 v[68:71], v[170:173], v[204:207], v[68:71]
	v_mfma_f32_16x16x32_bf16 v[52:55], v[178:181], v[204:207], v[52:55]
	v_mfma_f32_16x16x32_bf16 v[56:59], v[170:173], v[212:215], v[56:59]
	v_mfma_f32_16x16x32_bf16 v[40:43], v[178:181], v[212:215], v[40:43]
	v_mfma_f32_16x16x32_bf16 v[112:115], v[174:177], v[190:193], v[112:115]
	v_mfma_f32_16x16x32_bf16 v[96:99], v[182:185], v[190:193], v[96:99]
	v_mfma_f32_16x16x32_bf16 v[76:79], v[174:177], v[200:203], v[76:79]
	v_mfma_f32_16x16x32_bf16 v[64:67], v[182:185], v[200:203], v[64:67]
	v_mfma_f32_16x16x32_bf16 v[68:71], v[174:177], v[208:211], v[68:71]
	v_mfma_f32_16x16x32_bf16 v[52:55], v[182:185], v[208:211], v[52:55]
	v_mfma_f32_16x16x32_bf16 v[56:59], v[174:177], v[216:219], v[56:59]
	v_mfma_f32_16x16x32_bf16 v[40:43], v[182:185], v[216:219], v[40:43]
	s_setprio 0
	s_barrier
	s_add_i32 s30, s65, s4
	v_lshl_add_u64 v[166:167], s[42:43], 0, v[0:1]
	s_mov_b32 m0, s30
	ds_read_b128 v[186:189], v146 offset:16384
	ds_read_b128 v[190:193], v146 offset:17408
	ds_read_b128 v[194:197], v146 offset:18432
	ds_read_b128 v[200:203], v146 offset:19456
	ds_read_b128 v[204:207], v146 offset:20480
	ds_read_b128 v[208:211], v146 offset:21504
	ds_read_b128 v[212:215], v146 offset:22528
	ds_read_b128 v[216:219], v146 offset:23552
	global_load_lds_dwordx4 v[166:167], off
	s_add_i32 m0, s30, 0x2000
	s_add_u32 s30, s42, 0x160000
	v_lshl_add_u64 v[220:221], s[42:43], 0, v[30:31]
	s_addc_u32 s31, s43, 0
	s_add_i32 s65, s68, s4
	global_load_lds_dwordx4 v[220:221], off
	v_lshl_add_u64 v[222:223], s[30:31], 0, v[0:1]
	s_mov_b32 m0, s65
	v_lshl_add_u64 v[224:225], s[44:45], 0, v[132:133]
	global_load_lds_dwordx4 v[222:223], off
	v_lshl_add_u64 v[222:223], s[30:31], 0, v[30:31]
	s_add_i32 m0, s65, 0x2000
	s_nop 0
	global_load_lds_dwordx4 v[222:223], off
	v_lshl_add_u64 v[222:223], s[44:45], 0, v[134:135]
	s_mov_b32 m0, s28
	s_nop 0
	global_load_lds_dwordx4 v[222:223], off
	s_mov_b32 m0, s29
	s_nop 0
	global_load_lds_dwordx4 v[224:225], off
	s_waitcnt vmcnt(8)
	s_waitcnt lgkmcnt(0)
	s_barrier
	s_setprio 1
	s_waitcnt lgkmcnt(0)
	v_mfma_f32_16x16x32_bf16 v[88:91], v[148:151], v[186:189], v[88:91]
	v_mfma_f32_16x16x32_bf16 v[84:87], v[156:159], v[186:189], v[84:87]
	v_mfma_f32_16x16x32_bf16 v[80:83], v[148:151], v[194:197], v[80:83]
	v_mfma_f32_16x16x32_bf16 v[72:75], v[156:159], v[194:197], v[72:75]
	v_mfma_f32_16x16x32_bf16 v[60:63], v[148:151], v[204:207], v[60:63]
	v_mfma_f32_16x16x32_bf16 v[48:51], v[156:159], v[204:207], v[48:51]
	v_mfma_f32_16x16x32_bf16 v[36:39], v[148:151], v[212:215], v[36:39]
	v_mfma_f32_16x16x32_bf16 v[32:35], v[156:159], v[212:215], v[32:35]
	v_mfma_f32_16x16x32_bf16 v[88:91], v[152:155], v[190:193], v[88:91]
	v_mfma_f32_16x16x32_bf16 v[84:87], v[160:163], v[190:193], v[84:87]
	v_mfma_f32_16x16x32_bf16 v[80:83], v[152:155], v[200:203], v[80:83]
	v_mfma_f32_16x16x32_bf16 v[72:75], v[160:163], v[200:203], v[72:75]
	v_mfma_f32_16x16x32_bf16 v[60:63], v[152:155], v[208:211], v[60:63]
	v_mfma_f32_16x16x32_bf16 v[48:51], v[160:163], v[208:211], v[48:51]
	v_mfma_f32_16x16x32_bf16 v[36:39], v[152:155], v[216:219], v[36:39]
	v_mfma_f32_16x16x32_bf16 v[32:35], v[160:163], v[216:219], v[32:35]
	v_mfma_f32_16x16x32_bf16 v[44:47], v[170:173], v[186:189], v[44:47]
	v_mfma_f32_16x16x32_bf16 v[26:29], v[178:181], v[186:189], v[26:29]
	v_mfma_f32_16x16x32_bf16 v[22:25], v[170:173], v[194:197], v[22:25]
	v_mfma_f32_16x16x32_bf16 v[18:21], v[178:181], v[194:197], v[18:21]
	v_mfma_f32_16x16x32_bf16 v[14:17], v[170:173], v[204:207], v[14:17]
	v_mfma_f32_16x16x32_bf16 v[10:13], v[178:181], v[204:207], v[10:13]
	v_mfma_f32_16x16x32_bf16 v[6:9], v[170:173], v[212:215], v[6:9]
	v_mfma_f32_16x16x32_bf16 v[2:5], v[178:181], v[212:215], v[2:5]
	v_mfma_f32_16x16x32_bf16 v[44:47], v[174:177], v[190:193], v[44:47]
	v_mfma_f32_16x16x32_bf16 v[26:29], v[182:185], v[190:193], v[26:29]
	v_mfma_f32_16x16x32_bf16 v[22:25], v[174:177], v[200:203], v[22:25]
	v_mfma_f32_16x16x32_bf16 v[18:21], v[182:185], v[200:203], v[18:21]
	v_mfma_f32_16x16x32_bf16 v[14:17], v[174:177], v[208:211], v[14:17]
	v_mfma_f32_16x16x32_bf16 v[10:13], v[182:185], v[208:211], v[10:13]
	v_mfma_f32_16x16x32_bf16 v[6:9], v[174:177], v[216:219], v[6:9]
	v_mfma_f32_16x16x32_bf16 v[2:5], v[182:185], v[216:219], v[2:5]
	s_setprio 0
	s_barrier
	s_add_i32 s65, 0, 0x18000
	v_add_u32_e32 v147, s65, v145
	s_add_i32 s68, 0, 0x1c000
	ds_read_b128 v[148:151], v147
	ds_read_b128 v[152:155], v147 offset:1024
	ds_read_b128 v[156:159], v147 offset:2048
	ds_read_b128 v[160:163], v147 offset:3072
	v_add_u32_e32 v147, s68, v145
	ds_read_b128 v[170:173], v147
	ds_read_b128 v[174:177], v147 offset:1024
	ds_read_b128 v[178:181], v147 offset:2048
	ds_read_b128 v[182:185], v147 offset:3072
	s_add_u32 s30, s44, 0x160000
	s_addc_u32 s31, s45, 0
	s_mov_b32 m0, s49
	v_lshl_add_u64 v[226:227], s[30:31], 0, v[134:135]
	ds_read_b128 v[186:189], v146 offset:32768
	ds_read_b128 v[190:193], v146 offset:33792
	ds_read_b128 v[194:197], v146 offset:34816
	ds_read_b128 v[200:203], v146 offset:35840
	ds_read_b128 v[204:207], v146 offset:36864
	ds_read_b128 v[208:211], v146 offset:37888
	ds_read_b128 v[212:215], v146 offset:38912
	ds_read_b128 v[216:219], v146 offset:39936
	global_load_lds_dwordx4 v[226:227], off
	v_lshl_add_u64 v[226:227], s[30:31], 0, v[132:133]
	s_mov_b32 m0, s50
	s_nop 0
	global_load_lds_dwordx4 v[226:227], off
	s_waitcnt vmcnt(8)
	s_waitcnt lgkmcnt(0)
	s_barrier
	s_setprio 1
	s_waitcnt lgkmcnt(0)
	v_mfma_f32_16x16x32_bf16 v[128:131], v[148:151], v[186:189], v[128:131]
	v_mfma_f32_16x16x32_bf16 v[124:127], v[156:159], v[186:189], v[124:127]
	v_mfma_f32_16x16x32_bf16 v[120:123], v[148:151], v[194:197], v[120:123]
	v_mfma_f32_16x16x32_bf16 v[116:119], v[156:159], v[194:197], v[116:119]
	v_mfma_f32_16x16x32_bf16 v[108:111], v[148:151], v[204:207], v[108:111]
	v_mfma_f32_16x16x32_bf16 v[104:107], v[156:159], v[204:207], v[104:107]
	v_mfma_f32_16x16x32_bf16 v[100:103], v[148:151], v[212:215], v[100:103]
	v_mfma_f32_16x16x32_bf16 v[92:95], v[156:159], v[212:215], v[92:95]
	v_mfma_f32_16x16x32_bf16 v[128:131], v[152:155], v[190:193], v[128:131]
	v_mfma_f32_16x16x32_bf16 v[124:127], v[160:163], v[190:193], v[124:127]
	v_mfma_f32_16x16x32_bf16 v[120:123], v[152:155], v[200:203], v[120:123]
	v_mfma_f32_16x16x32_bf16 v[116:119], v[160:163], v[200:203], v[116:119]
	v_mfma_f32_16x16x32_bf16 v[108:111], v[152:155], v[208:211], v[108:111]
	v_mfma_f32_16x16x32_bf16 v[104:107], v[160:163], v[208:211], v[104:107]
	v_mfma_f32_16x16x32_bf16 v[100:103], v[152:155], v[216:219], v[100:103]
	v_mfma_f32_16x16x32_bf16 v[92:95], v[160:163], v[216:219], v[92:95]
	v_mfma_f32_16x16x32_bf16 v[112:115], v[170:173], v[186:189], v[112:115]
	v_mfma_f32_16x16x32_bf16 v[96:99], v[178:181], v[186:189], v[96:99]
	v_mfma_f32_16x16x32_bf16 v[76:79], v[170:173], v[194:197], v[76:79]
	v_mfma_f32_16x16x32_bf16 v[64:67], v[178:181], v[194:197], v[64:67]
	v_mfma_f32_16x16x32_bf16 v[68:71], v[170:173], v[204:207], v[68:71]
	v_mfma_f32_16x16x32_bf16 v[52:55], v[178:181], v[204:207], v[52:55]
	v_mfma_f32_16x16x32_bf16 v[56:59], v[170:173], v[212:215], v[56:59]
	v_mfma_f32_16x16x32_bf16 v[40:43], v[178:181], v[212:215], v[40:43]
	v_mfma_f32_16x16x32_bf16 v[112:115], v[174:177], v[190:193], v[112:115]
	v_mfma_f32_16x16x32_bf16 v[96:99], v[182:185], v[190:193], v[96:99]
	v_mfma_f32_16x16x32_bf16 v[76:79], v[174:177], v[200:203], v[76:79]
	v_mfma_f32_16x16x32_bf16 v[64:67], v[182:185], v[200:203], v[64:67]
	v_mfma_f32_16x16x32_bf16 v[68:71], v[174:177], v[208:211], v[68:71]
	v_mfma_f32_16x16x32_bf16 v[52:55], v[182:185], v[208:211], v[52:55]
	v_mfma_f32_16x16x32_bf16 v[56:59], v[174:177], v[216:219], v[56:59]
	v_mfma_f32_16x16x32_bf16 v[40:43], v[182:185], v[216:219], v[40:43]
	s_setprio 0
	s_barrier
	s_add_i32 s30, s65, s4
	v_lshl_add_u64 v[166:167], v[166:167], 0, s[24:25]
	s_mov_b32 m0, s30
	ds_read_b128 v[186:189], v146 offset:49152
	ds_read_b128 v[190:193], v146 offset:50176
	ds_read_b128 v[194:197], v146 offset:51200
	ds_read_b128 v[200:203], v146 offset:52224
	ds_read_b128 v[204:207], v146 offset:53248
	ds_read_b128 v[208:211], v146 offset:54272
	ds_read_b128 v[212:215], v146 offset:55296
	ds_read_b128 v[216:219], v146 offset:56320
	global_load_lds_dwordx4 v[166:167], off
	s_add_i32 m0, s30, 0x2000
	s_add_u32 s30, s42, 0x160080
	v_lshl_add_u64 v[166:167], v[220:221], 0, s[24:25]
	s_addc_u32 s31, s43, 0
	s_add_i32 s42, s68, s4
	global_load_lds_dwordx4 v[166:167], off
	v_lshl_add_u64 v[166:167], s[30:31], 0, v[0:1]
	s_mov_b32 m0, s42
	s_nop 0
	global_load_lds_dwordx4 v[166:167], off
	v_lshl_add_u64 v[166:167], s[30:31], 0, v[30:31]
	s_add_i32 m0, s42, 0x2000
	s_nop 0
	global_load_lds_dwordx4 v[166:167], off
	v_lshl_add_u64 v[166:167], v[222:223], 0, s[24:25]
	s_mov_b32 m0, s52
	s_nop 0
	global_load_lds_dwordx4 v[166:167], off
	v_lshl_add_u64 v[166:167], v[224:225], 0, s[24:25]
	s_mov_b32 m0, s53
	s_nop 0
	global_load_lds_dwordx4 v[166:167], off
	s_waitcnt vmcnt(8)
	s_waitcnt lgkmcnt(0)
	s_barrier
	s_setprio 1
	s_waitcnt lgkmcnt(0)
	v_mfma_f32_16x16x32_bf16 v[88:91], v[148:151], v[186:189], v[88:91]
	v_mfma_f32_16x16x32_bf16 v[84:87], v[156:159], v[186:189], v[84:87]
	v_mfma_f32_16x16x32_bf16 v[80:83], v[148:151], v[194:197], v[80:83]
	v_mfma_f32_16x16x32_bf16 v[72:75], v[156:159], v[194:197], v[72:75]
	v_mfma_f32_16x16x32_bf16 v[60:63], v[148:151], v[204:207], v[60:63]
	v_mfma_f32_16x16x32_bf16 v[48:51], v[156:159], v[204:207], v[48:51]
	v_mfma_f32_16x16x32_bf16 v[36:39], v[148:151], v[212:215], v[36:39]
	v_mfma_f32_16x16x32_bf16 v[32:35], v[156:159], v[212:215], v[32:35]
	v_mfma_f32_16x16x32_bf16 v[88:91], v[152:155], v[190:193], v[88:91]
	v_mfma_f32_16x16x32_bf16 v[84:87], v[160:163], v[190:193], v[84:87]
	v_mfma_f32_16x16x32_bf16 v[80:83], v[152:155], v[200:203], v[80:83]
	v_mfma_f32_16x16x32_bf16 v[72:75], v[160:163], v[200:203], v[72:75]
	v_mfma_f32_16x16x32_bf16 v[60:63], v[152:155], v[208:211], v[60:63]
	v_mfma_f32_16x16x32_bf16 v[48:51], v[160:163], v[208:211], v[48:51]
	v_mfma_f32_16x16x32_bf16 v[36:39], v[152:155], v[216:219], v[36:39]
	v_mfma_f32_16x16x32_bf16 v[32:35], v[160:163], v[216:219], v[32:35]
	v_mfma_f32_16x16x32_bf16 v[44:47], v[170:173], v[186:189], v[44:47]
	v_mfma_f32_16x16x32_bf16 v[26:29], v[178:181], v[186:189], v[26:29]
	v_mfma_f32_16x16x32_bf16 v[22:25], v[170:173], v[194:197], v[22:25]
	v_mfma_f32_16x16x32_bf16 v[18:21], v[178:181], v[194:197], v[18:21]
	v_mfma_f32_16x16x32_bf16 v[14:17], v[170:173], v[204:207], v[14:17]
	v_mfma_f32_16x16x32_bf16 v[10:13], v[178:181], v[204:207], v[10:13]
	v_mfma_f32_16x16x32_bf16 v[6:9], v[170:173], v[212:215], v[6:9]
	v_mfma_f32_16x16x32_bf16 v[2:5], v[178:181], v[212:215], v[2:5]
	v_mfma_f32_16x16x32_bf16 v[44:47], v[174:177], v[190:193], v[44:47]
	v_mfma_f32_16x16x32_bf16 v[26:29], v[182:185], v[190:193], v[26:29]
	v_mfma_f32_16x16x32_bf16 v[22:25], v[174:177], v[200:203], v[22:25]
	v_mfma_f32_16x16x32_bf16 v[18:21], v[182:185], v[200:203], v[18:21]
	v_mfma_f32_16x16x32_bf16 v[14:17], v[174:177], v[208:211], v[14:17]
	v_mfma_f32_16x16x32_bf16 v[10:13], v[182:185], v[208:211], v[10:13]
	v_mfma_f32_16x16x32_bf16 v[6:9], v[174:177], v[216:219], v[6:9]
	v_mfma_f32_16x16x32_bf16 v[2:5], v[182:185], v[216:219], v[2:5]
	s_setprio 0
	s_barrier
	s_add_i32 s64, s64, 2
	s_add_u32 s40, s40, 0x100
	s_addc_u32 s41, s41, 0
	s_cmpk_gt_u32 s64, 0x55
	s_cbranch_scc0 .LBB0_966
	s_add_u32 s40, s62, 0xffffff00
	s_addc_u32 s41, s63, -1
	s_and_b64 vcc, exec, s[38:39]
	s_cbranch_vccnz .LBB0_953
	v_mov_b32_e32 v2, 0
	s_mov_b32 s14, s55
	s_mov_b32 s48, s60
	s_mov_b64 s[20:21], s[22:23]
	s_mov_b32 s54, s61
	v_mov_b32_e32 v3, v2
	v_mov_b32_e32 v4, v2
	v_mov_b32_e32 v5, v2
	v_mov_b32_e32 v6, v2
	v_mov_b32_e32 v7, v2
	v_mov_b32_e32 v8, v2
	v_mov_b32_e32 v9, v2
	v_mov_b32_e32 v10, v2
	v_mov_b32_e32 v11, v2
	v_mov_b32_e32 v12, v2
	v_mov_b32_e32 v13, v2
	v_mov_b32_e32 v14, v2
	v_mov_b32_e32 v15, v2
	v_mov_b32_e32 v16, v2
	v_mov_b32_e32 v17, v2
	v_mov_b32_e32 v18, v2
	v_mov_b32_e32 v19, v2
	v_mov_b32_e32 v20, v2
	v_mov_b32_e32 v21, v2
	v_mov_b32_e32 v22, v2
	v_mov_b32_e32 v23, v2
	v_mov_b32_e32 v24, v2
	v_mov_b32_e32 v25, v2
	v_mov_b32_e32 v26, v2
	v_mov_b32_e32 v27, v2
	v_mov_b32_e32 v28, v2
	v_mov_b32_e32 v29, v2
	v_mov_b32_e32 v44, v2
	v_mov_b32_e32 v45, v2
	v_mov_b32_e32 v46, v2
	v_mov_b32_e32 v47, v2
	v_mov_b32_e32 v32, v2
	v_mov_b32_e32 v33, v2
	v_mov_b32_e32 v34, v2
	v_mov_b32_e32 v35, v2
	v_mov_b32_e32 v36, v2
	v_mov_b32_e32 v37, v2
	v_mov_b32_e32 v38, v2
	v_mov_b32_e32 v39, v2
	v_mov_b32_e32 v48, v2
	v_mov_b32_e32 v49, v2
	v_mov_b32_e32 v50, v2
	v_mov_b32_e32 v51, v2
	v_mov_b32_e32 v60, v2
	v_mov_b32_e32 v61, v2
	v_mov_b32_e32 v62, v2
	v_mov_b32_e32 v63, v2
	v_mov_b32_e32 v72, v2
	v_mov_b32_e32 v73, v2
	v_mov_b32_e32 v74, v2
	v_mov_b32_e32 v75, v2
	v_mov_b32_e32 v80, v2
	v_mov_b32_e32 v81, v2
	v_mov_b32_e32 v82, v2
	v_mov_b32_e32 v83, v2
	v_mov_b32_e32 v84, v2
	v_mov_b32_e32 v85, v2
	v_mov_b32_e32 v86, v2
	v_mov_b32_e32 v87, v2
	v_mov_b32_e32 v88, v2
	v_mov_b32_e32 v89, v2
	v_mov_b32_e32 v90, v2
	v_mov_b32_e32 v91, v2
	v_mov_b32_e32 v40, v2
	v_mov_b32_e32 v41, v2
	v_mov_b32_e32 v42, v2
	v_mov_b32_e32 v43, v2
	v_mov_b32_e32 v56, v2
	v_mov_b32_e32 v57, v2
	v_mov_b32_e32 v58, v2
	v_mov_b32_e32 v59, v2
	v_mov_b32_e32 v52, v2
	v_mov_b32_e32 v53, v2
	v_mov_b32_e32 v54, v2
	v_mov_b32_e32 v55, v2
	v_mov_b32_e32 v68, v2
	v_mov_b32_e32 v69, v2
	v_mov_b32_e32 v70, v2
	v_mov_b32_e32 v71, v2
	v_mov_b32_e32 v64, v2
	v_mov_b32_e32 v65, v2
	v_mov_b32_e32 v66, v2
	v_mov_b32_e32 v67, v2
	v_mov_b32_e32 v76, v2
	v_mov_b32_e32 v77, v2
	v_mov_b32_e32 v78, v2
	v_mov_b32_e32 v79, v2
	v_mov_b32_e32 v96, v2
	v_mov_b32_e32 v97, v2
	v_mov_b32_e32 v98, v2
	v_mov_b32_e32 v99, v2
	v_mov_b32_e32 v112, v2
	v_mov_b32_e32 v113, v2
	v_mov_b32_e32 v114, v2
	v_mov_b32_e32 v115, v2
	v_mov_b32_e32 v92, v2
	v_mov_b32_e32 v93, v2
	v_mov_b32_e32 v94, v2
	v_mov_b32_e32 v95, v2
	v_mov_b32_e32 v100, v2
	v_mov_b32_e32 v101, v2
	v_mov_b32_e32 v102, v2
	v_mov_b32_e32 v103, v2
	v_mov_b32_e32 v104, v2
	v_mov_b32_e32 v105, v2
	v_mov_b32_e32 v106, v2
	v_mov_b32_e32 v107, v2
	v_mov_b32_e32 v108, v2
	v_mov_b32_e32 v109, v2
	v_mov_b32_e32 v110, v2
	v_mov_b32_e32 v111, v2
	v_mov_b32_e32 v116, v2
	v_mov_b32_e32 v117, v2
	v_mov_b32_e32 v118, v2
	v_mov_b32_e32 v119, v2
	v_mov_b32_e32 v120, v2
	v_mov_b32_e32 v121, v2
	v_mov_b32_e32 v122, v2
	v_mov_b32_e32 v123, v2
	v_mov_b32_e32 v124, v2
	v_mov_b32_e32 v125, v2
	v_mov_b32_e32 v126, v2
	v_mov_b32_e32 v127, v2
	v_mov_b32_e32 v128, v2
	v_mov_b32_e32 v129, v2
	v_mov_b32_e32 v130, v2
	v_mov_b32_e32 v131, v2
	s_andn2_b64 vcc, exec, s[36:37]
	s_cbranch_vccnz .LBB0_954
